# P5 merge epilogue rewritten: gate loads rolled through a 4-group register ring with counted vmcnt and scalar row bases, overlapped with sigmoid math; packed f32 mul/add
# speedup vs baseline: 1.0276x; 1.0276x over previous
.LBB0_368:
	v_or_b32_e32 v130, 0x10000, v201
	v_add_u32_e32 v134, 0x10400, v201
	v_add_u32_e32 v138, 0x10800, v201
	v_add_u32_e32 v142, 0x10c00, v201
	ds_read_b128 v[130:133], v130
	ds_read_b128 v[134:137], v134
	ds_read_b128 v[138:141], v138
	ds_read_b128 v[142:145], v142
	s_add_u32 s10, s8, 0xfffc0080
	s_addc_u32 s11, s9, -1
	s_cmp_eq_u32 s29, 12
	s_cselect_b32 s11, s81, s11
	s_cselect_b32 s10, s80, s10
	s_cselect_b32 s53, s83, s28
	s_cselect_b32 s52, s82, s7
	v_lshl_add_u64 v[178:179], s[8:9], 0, v[212:213]
	s_add_i32 m0, s34, 0xc000
	ds_read_b128 v[146:149], v199
	ds_read_b128 v[150:153], v199 offset:1024
	ds_read_b128 v[154:157], v199 offset:2048
	ds_read_b128 v[158:161], v199 offset:3072
	ds_read_b128 v[162:165], v199 offset:4096
	ds_read_b128 v[166:169], v199 offset:5120
	ds_read_b128 v[170:173], v199 offset:6144
	ds_read_b128 v[174:177], v199 offset:7168
	global_load_lds_dwordx4 v[178:179], off
	v_lshl_add_u64 v[178:179], s[8:9], 0, v[214:215]
	s_add_i32 m0, s34, 0xe000
	s_nop 0
	global_load_lds_dwordx4 v[178:179], off
	s_waitcnt lgkmcnt(8)
	s_barrier
	s_waitcnt lgkmcnt(0)
	s_setprio 1
	s_waitcnt lgkmcnt(0)
	v_mfma_f32_16x16x32_bf16 v[126:129], v[130:133], v[146:149], v[126:129]
	v_mfma_f32_16x16x32_bf16 v[122:125], v[138:141], v[146:149], v[122:125]
	v_mfma_f32_16x16x32_bf16 v[118:121], v[130:133], v[154:157], v[118:121]
	v_mfma_f32_16x16x32_bf16 v[114:117], v[138:141], v[154:157], v[114:117]
	v_mfma_f32_16x16x32_bf16 v[110:113], v[130:133], v[162:165], v[110:113]
	v_mfma_f32_16x16x32_bf16 v[106:109], v[138:141], v[162:165], v[106:109]
	v_mfma_f32_16x16x32_bf16 v[102:105], v[130:133], v[170:173], v[102:105]
	v_mfma_f32_16x16x32_bf16 v[98:101], v[138:141], v[170:173], v[98:101]
	v_mfma_f32_16x16x32_bf16 v[126:129], v[134:137], v[150:153], v[126:129]
	v_mfma_f32_16x16x32_bf16 v[122:125], v[142:145], v[150:153], v[122:125]
	v_mfma_f32_16x16x32_bf16 v[118:121], v[134:137], v[158:161], v[118:121]
	v_mfma_f32_16x16x32_bf16 v[114:117], v[142:145], v[158:161], v[114:117]
	v_mfma_f32_16x16x32_bf16 v[110:113], v[134:137], v[166:169], v[110:113]
	v_mfma_f32_16x16x32_bf16 v[106:109], v[142:145], v[166:169], v[106:109]
	v_mfma_f32_16x16x32_bf16 v[102:105], v[134:137], v[174:177], v[102:105]
	v_mfma_f32_16x16x32_bf16 v[98:101], v[142:145], v[174:177], v[98:101]
	s_setprio 0
	s_barrier
	s_mov_b32 m0, s35
	v_or_b32_e32 v178, 0x14000, v201
	v_add_u32_e32 v182, 0x14400, v201
	v_add_u32_e32 v186, 0x14800, v201
	v_add_u32_e32 v190, 0x14c00, v201
	v_lshl_add_u64 v[216:217], s[52:53], 0, v[194:195]
	ds_read_b128 v[178:181], v178
	ds_read_b128 v[182:185], v182
	ds_read_b128 v[186:189], v186
	ds_read_b128 v[190:193], v190
	global_load_lds_dwordx4 v[216:217], off
	v_lshl_add_u64 v[218:219], s[52:53], 0, v[210:211]
	s_mov_b32 m0, s42
	s_nop 0
	global_load_lds_dwordx4 v[218:219], off
	s_barrier
	s_waitcnt lgkmcnt(0)
	s_setprio 1
	s_waitcnt lgkmcnt(0)
	v_mfma_f32_16x16x32_bf16 v[94:97], v[178:181], v[146:149], v[94:97]
	v_mfma_f32_16x16x32_bf16 v[90:93], v[186:189], v[146:149], v[90:93]
	v_mfma_f32_16x16x32_bf16 v[86:89], v[178:181], v[154:157], v[86:89]
	v_mfma_f32_16x16x32_bf16 v[82:85], v[186:189], v[154:157], v[82:85]
	v_mfma_f32_16x16x32_bf16 v[78:81], v[178:181], v[162:165], v[78:81]
	v_mfma_f32_16x16x32_bf16 v[74:77], v[186:189], v[162:165], v[74:77]
	v_mfma_f32_16x16x32_bf16 v[70:73], v[178:181], v[170:173], v[70:73]
	v_mfma_f32_16x16x32_bf16 v[66:69], v[186:189], v[170:173], v[66:69]
	v_mfma_f32_16x16x32_bf16 v[94:97], v[182:185], v[150:153], v[94:97]
	v_mfma_f32_16x16x32_bf16 v[90:93], v[190:193], v[150:153], v[90:93]
	v_mfma_f32_16x16x32_bf16 v[86:89], v[182:185], v[158:161], v[86:89]
	v_mfma_f32_16x16x32_bf16 v[82:85], v[190:193], v[158:161], v[82:85]
	v_mfma_f32_16x16x32_bf16 v[78:81], v[182:185], v[166:169], v[78:81]
	v_mfma_f32_16x16x32_bf16 v[74:77], v[190:193], v[166:169], v[74:77]
	v_mfma_f32_16x16x32_bf16 v[70:73], v[182:185], v[174:177], v[70:73]
	v_mfma_f32_16x16x32_bf16 v[66:69], v[190:193], v[174:177], v[66:69]
	s_setprio 0
	s_mov_b32 m0, s34
	v_lshl_add_u64 v[220:221], s[10:11], 0, v[206:207]
	s_barrier
	ds_read_b128 v[146:149], v199 offset:16384
	ds_read_b128 v[150:153], v199 offset:17408
	ds_read_b128 v[154:157], v199 offset:18432
	ds_read_b128 v[158:161], v199 offset:19456
	ds_read_b128 v[162:165], v199 offset:20480
	ds_read_b128 v[166:169], v199 offset:21504
	ds_read_b128 v[170:173], v199 offset:22528
	ds_read_b128 v[174:177], v199 offset:23552
	global_load_lds_dwordx4 v[220:221], off
	v_lshl_add_u64 v[222:223], s[10:11], 0, v[208:209]
	s_mov_b32 m0, s56
	s_nop 0
	global_load_lds_dwordx4 v[222:223], off
	s_barrier
	s_waitcnt lgkmcnt(0)
	s_setprio 1
	s_waitcnt lgkmcnt(0)
	v_mfma_f32_16x16x32_bf16 v[62:65], v[130:133], v[146:149], v[62:65]
	v_mfma_f32_16x16x32_bf16 v[58:61], v[138:141], v[146:149], v[58:61]
	v_mfma_f32_16x16x32_bf16 v[54:57], v[130:133], v[154:157], v[54:57]
	v_mfma_f32_16x16x32_bf16 v[50:53], v[138:141], v[154:157], v[50:53]
	v_mfma_f32_16x16x32_bf16 v[46:49], v[130:133], v[162:165], v[46:49]
	v_mfma_f32_16x16x32_bf16 v[42:45], v[138:141], v[162:165], v[42:45]
	v_mfma_f32_16x16x32_bf16 v[38:41], v[130:133], v[170:173], v[38:41]
	v_mfma_f32_16x16x32_bf16 v[34:37], v[138:141], v[170:173], v[34:37]
	v_mfma_f32_16x16x32_bf16 v[62:65], v[134:137], v[150:153], v[62:65]
	v_mfma_f32_16x16x32_bf16 v[58:61], v[142:145], v[150:153], v[58:61]
	v_mfma_f32_16x16x32_bf16 v[54:57], v[134:137], v[158:161], v[54:57]
	v_mfma_f32_16x16x32_bf16 v[50:53], v[142:145], v[158:161], v[50:53]
	v_mfma_f32_16x16x32_bf16 v[46:49], v[134:137], v[166:169], v[46:49]
	v_mfma_f32_16x16x32_bf16 v[42:45], v[142:145], v[166:169], v[42:45]
	v_mfma_f32_16x16x32_bf16 v[38:41], v[134:137], v[174:177], v[38:41]
	v_mfma_f32_16x16x32_bf16 v[34:37], v[142:145], v[174:177], v[34:37]
	s_setprio 0
	s_barrier
	s_add_u32 s86, s52, 0x40000
	s_addc_u32 s87, s53, 0
	s_mov_b32 m0, s57
	v_lshl_add_u64 v[130:131], s[86:87], 0, v[194:195]
	global_load_lds_dwordx4 v[130:131], off
	v_lshl_add_u64 v[130:131], s[86:87], 0, v[210:211]
	s_mov_b32 m0, s67
	s_nop 0
	global_load_lds_dwordx4 v[130:131], off
	s_waitcnt vmcnt(6)
	s_barrier
	s_setprio 1
	v_mfma_f32_16x16x32_bf16 v[30:33], v[178:181], v[146:149], v[30:33]
	v_mfma_f32_16x16x32_bf16 v[26:29], v[186:189], v[146:149], v[26:29]
	v_mfma_f32_16x16x32_bf16 v[22:25], v[178:181], v[154:157], v[22:25]
	v_mfma_f32_16x16x32_bf16 v[18:21], v[186:189], v[154:157], v[18:21]
	v_mfma_f32_16x16x32_bf16 v[14:17], v[178:181], v[162:165], v[14:17]
	v_mfma_f32_16x16x32_bf16 v[10:13], v[186:189], v[162:165], v[10:13]
	v_mfma_f32_16x16x32_bf16 v[6:9], v[178:181], v[170:173], v[6:9]
	v_mfma_f32_16x16x32_bf16 v[2:5], v[186:189], v[170:173], v[2:5]
	v_mfma_f32_16x16x32_bf16 v[30:33], v[182:185], v[150:153], v[30:33]
	v_mfma_f32_16x16x32_bf16 v[26:29], v[190:193], v[150:153], v[26:29]
	v_mfma_f32_16x16x32_bf16 v[22:25], v[182:185], v[158:161], v[22:25]
	v_mfma_f32_16x16x32_bf16 v[18:21], v[190:193], v[158:161], v[18:21]
	v_mfma_f32_16x16x32_bf16 v[14:17], v[182:185], v[166:169], v[14:17]
	v_mfma_f32_16x16x32_bf16 v[10:13], v[190:193], v[166:169], v[10:13]
	v_mfma_f32_16x16x32_bf16 v[6:9], v[182:185], v[174:177], v[6:9]
	v_mfma_f32_16x16x32_bf16 v[2:5], v[190:193], v[174:177], v[2:5]
	s_setprio 0
	v_or_b32_e32 v130, 0x18000, v201
	v_add_u32_e32 v134, 0x18400, v201
	v_add_u32_e32 v138, 0x18800, v201
	v_add_u32_e32 v142, 0x18c00, v201
	s_barrier
	ds_read_b128 v[130:133], v130
	ds_read_b128 v[134:137], v134
	ds_read_b128 v[138:141], v138
	ds_read_b128 v[142:145], v142
	s_add_u32 s10, s10, 0x40000
	s_addc_u32 s11, s11, 0
	s_mov_b32 m0, s70
	v_lshl_add_u64 v[178:179], s[10:11], 0, v[206:207]
	ds_read_b128 v[146:149], v199 offset:32768
	ds_read_b128 v[150:153], v199 offset:33792
	ds_read_b128 v[154:157], v199 offset:34816
	ds_read_b128 v[158:161], v199 offset:35840
	ds_read_b128 v[162:165], v199 offset:36864
	ds_read_b128 v[166:169], v199 offset:37888
	ds_read_b128 v[170:173], v199 offset:38912
	ds_read_b128 v[174:177], v199 offset:39936
	global_load_lds_dwordx4 v[178:179], off
	v_lshl_add_u64 v[178:179], s[10:11], 0, v[208:209]
	s_mov_b32 m0, s71
	s_nop 0
	global_load_lds_dwordx4 v[178:179], off
	s_waitcnt lgkmcnt(8)
	s_barrier
	s_waitcnt lgkmcnt(0)
	s_setprio 1
	s_waitcnt lgkmcnt(0)
	v_mfma_f32_16x16x32_bf16 v[126:129], v[130:133], v[146:149], v[126:129]
	v_mfma_f32_16x16x32_bf16 v[122:125], v[138:141], v[146:149], v[122:125]
	v_mfma_f32_16x16x32_bf16 v[118:121], v[130:133], v[154:157], v[118:121]
	v_mfma_f32_16x16x32_bf16 v[114:117], v[138:141], v[154:157], v[114:117]
	v_mfma_f32_16x16x32_bf16 v[110:113], v[130:133], v[162:165], v[110:113]
	v_mfma_f32_16x16x32_bf16 v[106:109], v[138:141], v[162:165], v[106:109]
	v_mfma_f32_16x16x32_bf16 v[102:105], v[130:133], v[170:173], v[102:105]
	v_mfma_f32_16x16x32_bf16 v[98:101], v[138:141], v[170:173], v[98:101]
	v_mfma_f32_16x16x32_bf16 v[126:129], v[134:137], v[150:153], v[126:129]
	v_mfma_f32_16x16x32_bf16 v[122:125], v[142:145], v[150:153], v[122:125]
	v_mfma_f32_16x16x32_bf16 v[118:121], v[134:137], v[158:161], v[118:121]
	v_mfma_f32_16x16x32_bf16 v[114:117], v[142:145], v[158:161], v[114:117]
	v_mfma_f32_16x16x32_bf16 v[110:113], v[134:137], v[166:169], v[110:113]
	v_mfma_f32_16x16x32_bf16 v[106:109], v[142:145], v[166:169], v[106:109]
	v_mfma_f32_16x16x32_bf16 v[102:105], v[134:137], v[174:177], v[102:105]
	v_mfma_f32_16x16x32_bf16 v[98:101], v[142:145], v[174:177], v[98:101]
	s_setprio 0
	s_barrier
	s_mov_b32 m0, s78
	v_or_b32_e32 v178, 0x1c000, v201
	v_add_u32_e32 v182, 0x1c400, v201
	v_add_u32_e32 v186, 0x1c800, v201
	v_add_u32_e32 v190, 0x1cc00, v201
	v_lshl_add_u64 v[216:217], v[216:217], 0, s[76:77]
	ds_read_b128 v[178:181], v178
	ds_read_b128 v[182:185], v182
	ds_read_b128 v[186:189], v186
	ds_read_b128 v[190:193], v190
	global_load_lds_dwordx4 v[216:217], off
	v_lshl_add_u64 v[216:217], v[218:219], 0, s[76:77]
	s_mov_b32 m0, s79
	s_nop 0
	global_load_lds_dwordx4 v[216:217], off
	s_barrier
	s_waitcnt lgkmcnt(0)
	s_setprio 1
	s_waitcnt lgkmcnt(0)
	v_mfma_f32_16x16x32_bf16 v[94:97], v[178:181], v[146:149], v[94:97]
	v_mfma_f32_16x16x32_bf16 v[90:93], v[186:189], v[146:149], v[90:93]
	v_mfma_f32_16x16x32_bf16 v[86:89], v[178:181], v[154:157], v[86:89]
	v_mfma_f32_16x16x32_bf16 v[82:85], v[186:189], v[154:157], v[82:85]
	v_mfma_f32_16x16x32_bf16 v[78:81], v[178:181], v[162:165], v[78:81]
	v_mfma_f32_16x16x32_bf16 v[74:77], v[186:189], v[162:165], v[74:77]
	v_mfma_f32_16x16x32_bf16 v[70:73], v[178:181], v[170:173], v[70:73]
	v_mfma_f32_16x16x32_bf16 v[66:69], v[186:189], v[170:173], v[66:69]
	v_mfma_f32_16x16x32_bf16 v[94:97], v[182:185], v[150:153], v[94:97]
	v_mfma_f32_16x16x32_bf16 v[90:93], v[190:193], v[150:153], v[90:93]
	v_mfma_f32_16x16x32_bf16 v[86:89], v[182:185], v[158:161], v[86:89]
	v_mfma_f32_16x16x32_bf16 v[82:85], v[190:193], v[158:161], v[82:85]
	v_mfma_f32_16x16x32_bf16 v[78:81], v[182:185], v[166:169], v[78:81]
	v_mfma_f32_16x16x32_bf16 v[74:77], v[190:193], v[166:169], v[74:77]
	v_mfma_f32_16x16x32_bf16 v[70:73], v[182:185], v[174:177], v[70:73]
	v_mfma_f32_16x16x32_bf16 v[66:69], v[190:193], v[174:177], v[66:69]
	s_setprio 0
	s_mov_b32 m0, s26
	v_lshl_add_u64 v[216:217], v[220:221], 0, s[76:77]
	s_barrier
	ds_read_b128 v[146:149], v199 offset:49152
	ds_read_b128 v[150:153], v199 offset:50176
	ds_read_b128 v[154:157], v199 offset:51200
	ds_read_b128 v[158:161], v199 offset:52224
	ds_read_b128 v[162:165], v199 offset:53248
	ds_read_b128 v[166:169], v199 offset:54272
	ds_read_b128 v[170:173], v199 offset:55296
	ds_read_b128 v[174:177], v199 offset:56320
	global_load_lds_dwordx4 v[216:217], off
	v_lshl_add_u64 v[216:217], v[222:223], 0, s[76:77]
	s_mov_b32 m0, s4
	s_nop 0
	global_load_lds_dwordx4 v[216:217], off
	s_barrier
	s_waitcnt lgkmcnt(0)
	s_setprio 1
	s_waitcnt lgkmcnt(0)
	v_mfma_f32_16x16x32_bf16 v[62:65], v[130:133], v[146:149], v[62:65]
	v_mfma_f32_16x16x32_bf16 v[58:61], v[138:141], v[146:149], v[58:61]
	v_mfma_f32_16x16x32_bf16 v[54:57], v[130:133], v[154:157], v[54:57]
	v_mfma_f32_16x16x32_bf16 v[50:53], v[138:141], v[154:157], v[50:53]
	v_mfma_f32_16x16x32_bf16 v[46:49], v[130:133], v[162:165], v[46:49]
	v_mfma_f32_16x16x32_bf16 v[42:45], v[138:141], v[162:165], v[42:45]
	v_mfma_f32_16x16x32_bf16 v[38:41], v[130:133], v[170:173], v[38:41]
	v_mfma_f32_16x16x32_bf16 v[34:37], v[138:141], v[170:173], v[34:37]
	v_mfma_f32_16x16x32_bf16 v[62:65], v[134:137], v[150:153], v[62:65]
	v_mfma_f32_16x16x32_bf16 v[58:61], v[142:145], v[150:153], v[58:61]
	v_mfma_f32_16x16x32_bf16 v[54:57], v[134:137], v[158:161], v[54:57]
	v_mfma_f32_16x16x32_bf16 v[50:53], v[142:145], v[158:161], v[50:53]
	v_mfma_f32_16x16x32_bf16 v[46:49], v[134:137], v[166:169], v[46:49]
	v_mfma_f32_16x16x32_bf16 v[42:45], v[142:145], v[166:169], v[42:45]
	v_mfma_f32_16x16x32_bf16 v[38:41], v[134:137], v[174:177], v[38:41]
	v_mfma_f32_16x16x32_bf16 v[34:37], v[142:145], v[174:177], v[34:37]
	s_setprio 0
	s_barrier
	s_add_u32 s10, s52, 0x40080
	s_addc_u32 s11, s53, 0
	s_mov_b32 m0, s5
	v_lshl_add_u64 v[130:131], s[10:11], 0, v[194:195]
	global_load_lds_dwordx4 v[130:131], off
	v_lshl_add_u64 v[130:131], s[10:11], 0, v[210:211]
	s_mov_b32 m0, s58
	s_nop 0
	global_load_lds_dwordx4 v[130:131], off
	s_waitcnt vmcnt(6)
	s_barrier
	s_setprio 1
	v_mfma_f32_16x16x32_bf16 v[30:33], v[178:181], v[146:149], v[30:33]
	v_mfma_f32_16x16x32_bf16 v[26:29], v[186:189], v[146:149], v[26:29]
	v_mfma_f32_16x16x32_bf16 v[22:25], v[178:181], v[154:157], v[22:25]
	v_mfma_f32_16x16x32_bf16 v[18:21], v[186:189], v[154:157], v[18:21]
	v_mfma_f32_16x16x32_bf16 v[14:17], v[178:181], v[162:165], v[14:17]
	v_mfma_f32_16x16x32_bf16 v[10:13], v[186:189], v[162:165], v[10:13]
	v_mfma_f32_16x16x32_bf16 v[6:9], v[178:181], v[170:173], v[6:9]
	v_mfma_f32_16x16x32_bf16 v[2:5], v[186:189], v[170:173], v[2:5]
	v_mfma_f32_16x16x32_bf16 v[30:33], v[182:185], v[150:153], v[30:33]
	v_mfma_f32_16x16x32_bf16 v[26:29], v[190:193], v[150:153], v[26:29]
	v_mfma_f32_16x16x32_bf16 v[22:25], v[182:185], v[158:161], v[22:25]
	v_mfma_f32_16x16x32_bf16 v[18:21], v[190:193], v[158:161], v[18:21]
	v_mfma_f32_16x16x32_bf16 v[14:17], v[182:185], v[166:169], v[14:17]
	v_mfma_f32_16x16x32_bf16 v[10:13], v[190:193], v[166:169], v[10:13]
	v_mfma_f32_16x16x32_bf16 v[6:9], v[182:185], v[174:177], v[6:9]
	v_mfma_f32_16x16x32_bf16 v[2:5], v[190:193], v[174:177], v[2:5]
	s_setprio 0
	s_add_i32 s29, s29, 2
	s_add_u32 s8, s8, 0x100
	s_addc_u32 s9, s9, 0
	s_add_u32 s7, s7, 0x100
	s_addc_u32 s28, s28, 0
	s_cmp_gt_u32 s29, 13
	s_barrier
	s_cbranch_scc0 .LBB0_368
	s_cmp_gt_i32 s95, 1
	s_cselect_b64 s[52:53], -1, 0
	s_mul_i32 s7, s6, 0x680000
	s_lshl_b32 s8, s95, 12
	s_lshl_b32 s9, s54, 9
	s_add_i32 s7, s7, s8
	s_add_i32 s7, s7, s9
	s_add_i32 s7, s7, 0x3800
	s_add_u32 s20, s50, s7
	s_addc_u32 s21, s51, 0
	s_lshl_b32 s7, s6, 20
	s_add_i32 s7, s7, s9
	s_add_u32 s10, s96, s7
	s_addc_u32 s11, s97, 0
	s_mov_b32 s86, 0xbfb8aa3b
	s_mov_b32 s87, 0xbfb8aa3b
	v_mul_u32_u24_e32 v253, 0x6800, v197
	v_lshlrev_b32_e32 v255, 12, v197
	v_lshl_add_u32 v253, v203, 1, v253
	v_lshl_add_u32 v255, v203, 1, v255
	v_add_u32_e32 v254, 0x1000, v253
	s_cmp_eq_u32 s95, 2
	s_cbranch_scc1 .Lem_br2
	global_load_dwordx4 v[130:133], v253, s[20:21]
	global_load_dwordx4 v[134:137], v254, s[20:21]
	global_load_dwordx4 v[138:141], v253, s[20:21] offset:256
	global_load_dwordx4 v[142:145], v254, s[20:21] offset:256
	s_add_u32 s28, s20, 0x68000
	s_addc_u32 s29, s21, 0
	global_load_dwordx4 v[146:149], v253, s[28:29]
	global_load_dwordx4 v[150:153], v254, s[28:29]
	global_load_dwordx4 v[154:157], v253, s[28:29] offset:256
	global_load_dwordx4 v[158:161], v254, s[28:29] offset:256
	s_add_u32 s28, s20, 0xd0000
	s_addc_u32 s29, s21, 0
	global_load_dwordx4 v[162:165], v253, s[28:29]
	global_load_dwordx4 v[166:169], v254, s[28:29]
	global_load_dwordx4 v[170:173], v253, s[28:29] offset:256
	global_load_dwordx4 v[174:177], v254, s[28:29] offset:256
	s_add_u32 s28, s20, 0x138000
	s_addc_u32 s29, s21, 0
	global_load_dwordx4 v[178:181], v253, s[28:29]
	global_load_dwordx4 v[182:185], v254, s[28:29]
	global_load_dwordx4 v[186:189], v253, s[28:29] offset:256
	global_load_dwordx4 v[190:193], v254, s[28:29] offset:256
	s_waitcnt vmcnt(12)
	v_lshlrev_b32_e32 v216, 16, v130
	v_and_b32_e32 v217, 0xffff0000, v130
	v_lshlrev_b32_e32 v218, 16, v131
	v_and_b32_e32 v219, 0xffff0000, v131
	v_lshlrev_b32_e32 v220, 16, v132
	v_and_b32_e32 v221, 0xffff0000, v132
	v_lshlrev_b32_e32 v222, 16, v133
	v_and_b32_e32 v223, 0xffff0000, v133
	v_pk_mul_f32 v[216:217], v[216:217], s[86:87] op_sel_hi:[1,0]
	v_pk_mul_f32 v[218:219], v[218:219], s[86:87] op_sel_hi:[1,0]
	v_pk_mul_f32 v[220:221], v[220:221], s[86:87] op_sel_hi:[1,0]
	v_pk_mul_f32 v[222:223], v[222:223], s[86:87] op_sel_hi:[1,0]
	v_exp_f32_e32 v216, v216
	v_exp_f32_e32 v217, v217
	v_exp_f32_e32 v218, v218
	v_exp_f32_e32 v219, v219
	v_exp_f32_e32 v220, v220
	v_exp_f32_e32 v221, v221
	v_exp_f32_e32 v222, v222
	v_exp_f32_e32 v223, v223
	v_pk_add_f32 v[216:217], v[216:217], 1.0 op_sel_hi:[1,0]
	v_pk_add_f32 v[218:219], v[218:219], 1.0 op_sel_hi:[1,0]
	v_pk_add_f32 v[220:221], v[220:221], 1.0 op_sel_hi:[1,0]
	v_pk_add_f32 v[222:223], v[222:223], 1.0 op_sel_hi:[1,0]
	v_rcp_f32_e32 v216, v216
	v_rcp_f32_e32 v217, v217
	v_rcp_f32_e32 v218, v218
	v_rcp_f32_e32 v219, v219
	v_rcp_f32_e32 v220, v220
	v_rcp_f32_e32 v221, v221
	v_rcp_f32_e32 v222, v222
	v_rcp_f32_e32 v223, v223
	v_lshlrev_b32_e32 v242, 16, v134
	v_and_b32_e32 v243, 0xffff0000, v134
	v_lshlrev_b32_e32 v244, 16, v135
	v_and_b32_e32 v245, 0xffff0000, v135
	v_lshlrev_b32_e32 v246, 16, v136
	v_and_b32_e32 v247, 0xffff0000, v136
	v_lshlrev_b32_e32 v248, 16, v137
	v_and_b32_e32 v249, 0xffff0000, v137
	v_pk_mul_f32 v[242:243], v[242:243], s[86:87] op_sel_hi:[1,0]
	v_pk_mul_f32 v[244:245], v[244:245], s[86:87] op_sel_hi:[1,0]
	v_pk_mul_f32 v[246:247], v[246:247], s[86:87] op_sel_hi:[1,0]
	v_pk_mul_f32 v[248:249], v[248:249], s[86:87] op_sel_hi:[1,0]
	v_exp_f32_e32 v242, v242
	v_exp_f32_e32 v243, v243
	v_exp_f32_e32 v244, v244
	v_exp_f32_e32 v245, v245
	v_exp_f32_e32 v246, v246
	v_exp_f32_e32 v247, v247
	v_exp_f32_e32 v248, v248
	v_exp_f32_e32 v249, v249
	v_pk_add_f32 v[242:243], v[242:243], 1.0 op_sel_hi:[1,0]
	v_pk_add_f32 v[244:245], v[244:245], 1.0 op_sel_hi:[1,0]
	v_pk_add_f32 v[246:247], v[246:247], 1.0 op_sel_hi:[1,0]
	v_pk_add_f32 v[248:249], v[248:249], 1.0 op_sel_hi:[1,0]
	v_pk_mul_f32 v[216:217], v[216:217], v[242:243]
	v_pk_mul_f32 v[218:219], v[218:219], v[244:245]
	v_pk_mul_f32 v[220:221], v[220:221], v[246:247]
	v_pk_mul_f32 v[222:223], v[222:223], v[248:249]
	v_pk_mul_f32 v[126:127], v[126:127], v[216:217]
	v_pk_mul_f32 v[128:129], v[128:129], v[218:219]
	v_pk_mul_f32 v[122:123], v[122:123], v[220:221]
	v_pk_mul_f32 v[124:125], v[124:125], v[222:223]
	v_lshlrev_b32_e32 v216, 16, v138
	v_and_b32_e32 v217, 0xffff0000, v138
	v_lshlrev_b32_e32 v218, 16, v139
	v_and_b32_e32 v219, 0xffff0000, v139
	v_lshlrev_b32_e32 v220, 16, v140
	v_and_b32_e32 v221, 0xffff0000, v140
	v_lshlrev_b32_e32 v222, 16, v141
	v_and_b32_e32 v223, 0xffff0000, v141
	v_pk_mul_f32 v[216:217], v[216:217], s[86:87] op_sel_hi:[1,0]
	v_pk_mul_f32 v[218:219], v[218:219], s[86:87] op_sel_hi:[1,0]
	v_pk_mul_f32 v[220:221], v[220:221], s[86:87] op_sel_hi:[1,0]
	v_pk_mul_f32 v[222:223], v[222:223], s[86:87] op_sel_hi:[1,0]
	v_exp_f32_e32 v216, v216
	v_exp_f32_e32 v217, v217
	v_exp_f32_e32 v218, v218
	v_exp_f32_e32 v219, v219
	v_exp_f32_e32 v220, v220
	v_exp_f32_e32 v221, v221
	v_exp_f32_e32 v222, v222
	v_exp_f32_e32 v223, v223
	v_pk_add_f32 v[216:217], v[216:217], 1.0 op_sel_hi:[1,0]
	v_pk_add_f32 v[218:219], v[218:219], 1.0 op_sel_hi:[1,0]
	v_pk_add_f32 v[220:221], v[220:221], 1.0 op_sel_hi:[1,0]
	v_pk_add_f32 v[222:223], v[222:223], 1.0 op_sel_hi:[1,0]
	v_rcp_f32_e32 v216, v216
	v_rcp_f32_e32 v217, v217
	v_rcp_f32_e32 v218, v218
	v_rcp_f32_e32 v219, v219
	v_rcp_f32_e32 v220, v220
	v_rcp_f32_e32 v221, v221
	v_rcp_f32_e32 v222, v222
	v_rcp_f32_e32 v223, v223
	v_lshlrev_b32_e32 v242, 16, v142
	v_and_b32_e32 v243, 0xffff0000, v142
	v_lshlrev_b32_e32 v244, 16, v143
	v_and_b32_e32 v245, 0xffff0000, v143
	v_lshlrev_b32_e32 v246, 16, v144
	v_and_b32_e32 v247, 0xffff0000, v144
	v_lshlrev_b32_e32 v248, 16, v145
	v_and_b32_e32 v249, 0xffff0000, v145
	v_pk_mul_f32 v[242:243], v[242:243], s[86:87] op_sel_hi:[1,0]
	v_pk_mul_f32 v[244:245], v[244:245], s[86:87] op_sel_hi:[1,0]
	v_pk_mul_f32 v[246:247], v[246:247], s[86:87] op_sel_hi:[1,0]
	v_pk_mul_f32 v[248:249], v[248:249], s[86:87] op_sel_hi:[1,0]
	v_exp_f32_e32 v242, v242
	v_exp_f32_e32 v243, v243
	v_exp_f32_e32 v244, v244
	v_exp_f32_e32 v245, v245
	v_exp_f32_e32 v246, v246
	v_exp_f32_e32 v247, v247
	v_exp_f32_e32 v248, v248
	v_exp_f32_e32 v249, v249
	v_pk_add_f32 v[242:243], v[242:243], 1.0 op_sel_hi:[1,0]
	v_pk_add_f32 v[244:245], v[244:245], 1.0 op_sel_hi:[1,0]
	v_pk_add_f32 v[246:247], v[246:247], 1.0 op_sel_hi:[1,0]
	v_pk_add_f32 v[248:249], v[248:249], 1.0 op_sel_hi:[1,0]
	v_pk_mul_f32 v[216:217], v[216:217], v[242:243]
	v_pk_mul_f32 v[218:219], v[218:219], v[244:245]
	v_pk_mul_f32 v[220:221], v[220:221], v[246:247]
	v_pk_mul_f32 v[222:223], v[222:223], v[248:249]
	v_pk_mul_f32 v[94:95], v[94:95], v[216:217]
	v_pk_mul_f32 v[96:97], v[96:97], v[218:219]
	v_pk_mul_f32 v[90:91], v[90:91], v[220:221]
	v_pk_mul_f32 v[92:93], v[92:93], v[222:223]
	s_add_u32 s28, s20, 0x340000
	s_addc_u32 s29, s21, 0
	global_load_dwordx4 v[130:133], v253, s[28:29]
	global_load_dwordx4 v[134:137], v254, s[28:29]
	global_load_dwordx4 v[138:141], v253, s[28:29] offset:256
	global_load_dwordx4 v[142:145], v254, s[28:29] offset:256
	s_waitcnt vmcnt(12)
	v_lshlrev_b32_e32 v216, 16, v146
	v_and_b32_e32 v217, 0xffff0000, v146
	v_lshlrev_b32_e32 v218, 16, v147
	v_and_b32_e32 v219, 0xffff0000, v147
	v_lshlrev_b32_e32 v220, 16, v148
	v_and_b32_e32 v221, 0xffff0000, v148
	v_lshlrev_b32_e32 v222, 16, v149
	v_and_b32_e32 v223, 0xffff0000, v149
	v_pk_mul_f32 v[216:217], v[216:217], s[86:87] op_sel_hi:[1,0]
	v_pk_mul_f32 v[218:219], v[218:219], s[86:87] op_sel_hi:[1,0]
	v_pk_mul_f32 v[220:221], v[220:221], s[86:87] op_sel_hi:[1,0]
	v_pk_mul_f32 v[222:223], v[222:223], s[86:87] op_sel_hi:[1,0]
	v_exp_f32_e32 v216, v216
	v_exp_f32_e32 v217, v217
	v_exp_f32_e32 v218, v218
	v_exp_f32_e32 v219, v219
	v_exp_f32_e32 v220, v220
	v_exp_f32_e32 v221, v221
	v_exp_f32_e32 v222, v222
	v_exp_f32_e32 v223, v223
	v_pk_add_f32 v[216:217], v[216:217], 1.0 op_sel_hi:[1,0]
	v_pk_add_f32 v[218:219], v[218:219], 1.0 op_sel_hi:[1,0]
	v_pk_add_f32 v[220:221], v[220:221], 1.0 op_sel_hi:[1,0]
	v_pk_add_f32 v[222:223], v[222:223], 1.0 op_sel_hi:[1,0]
	v_rcp_f32_e32 v216, v216
	v_rcp_f32_e32 v217, v217
	v_rcp_f32_e32 v218, v218
	v_rcp_f32_e32 v219, v219
	v_rcp_f32_e32 v220, v220
	v_rcp_f32_e32 v221, v221
	v_rcp_f32_e32 v222, v222
	v_rcp_f32_e32 v223, v223
	v_lshlrev_b32_e32 v242, 16, v150
	v_and_b32_e32 v243, 0xffff0000, v150
	v_lshlrev_b32_e32 v244, 16, v151
	v_and_b32_e32 v245, 0xffff0000, v151
	v_lshlrev_b32_e32 v246, 16, v152
	v_and_b32_e32 v247, 0xffff0000, v152
	v_lshlrev_b32_e32 v248, 16, v153
	v_and_b32_e32 v249, 0xffff0000, v153
	v_pk_mul_f32 v[242:243], v[242:243], s[86:87] op_sel_hi:[1,0]
	v_pk_mul_f32 v[244:245], v[244:245], s[86:87] op_sel_hi:[1,0]
	v_pk_mul_f32 v[246:247], v[246:247], s[86:87] op_sel_hi:[1,0]
	v_pk_mul_f32 v[248:249], v[248:249], s[86:87] op_sel_hi:[1,0]
	v_exp_f32_e32 v242, v242
	v_exp_f32_e32 v243, v243
	v_exp_f32_e32 v244, v244
	v_exp_f32_e32 v245, v245
	v_exp_f32_e32 v246, v246
	v_exp_f32_e32 v247, v247
	v_exp_f32_e32 v248, v248
	v_exp_f32_e32 v249, v249
	v_pk_add_f32 v[242:243], v[242:243], 1.0 op_sel_hi:[1,0]
	v_pk_add_f32 v[244:245], v[244:245], 1.0 op_sel_hi:[1,0]
	v_pk_add_f32 v[246:247], v[246:247], 1.0 op_sel_hi:[1,0]
	v_pk_add_f32 v[248:249], v[248:249], 1.0 op_sel_hi:[1,0]
	v_pk_mul_f32 v[216:217], v[216:217], v[242:243]
	v_pk_mul_f32 v[218:219], v[218:219], v[244:245]
	v_pk_mul_f32 v[220:221], v[220:221], v[246:247]
	v_pk_mul_f32 v[222:223], v[222:223], v[248:249]
	v_pk_mul_f32 v[118:119], v[118:119], v[216:217]
	v_pk_mul_f32 v[120:121], v[120:121], v[218:219]
	v_pk_mul_f32 v[114:115], v[114:115], v[220:221]
	v_pk_mul_f32 v[116:117], v[116:117], v[222:223]
	v_lshlrev_b32_e32 v216, 16, v154
	v_and_b32_e32 v217, 0xffff0000, v154
	v_lshlrev_b32_e32 v218, 16, v155
	v_and_b32_e32 v219, 0xffff0000, v155
	v_lshlrev_b32_e32 v220, 16, v156
	v_and_b32_e32 v221, 0xffff0000, v156
	v_lshlrev_b32_e32 v222, 16, v157
	v_and_b32_e32 v223, 0xffff0000, v157
	v_pk_mul_f32 v[216:217], v[216:217], s[86:87] op_sel_hi:[1,0]
	v_pk_mul_f32 v[218:219], v[218:219], s[86:87] op_sel_hi:[1,0]
	v_pk_mul_f32 v[220:221], v[220:221], s[86:87] op_sel_hi:[1,0]
	v_pk_mul_f32 v[222:223], v[222:223], s[86:87] op_sel_hi:[1,0]
	v_exp_f32_e32 v216, v216
	v_exp_f32_e32 v217, v217
	v_exp_f32_e32 v218, v218
	v_exp_f32_e32 v219, v219
	v_exp_f32_e32 v220, v220
	v_exp_f32_e32 v221, v221
	v_exp_f32_e32 v222, v222
	v_exp_f32_e32 v223, v223
	v_pk_add_f32 v[216:217], v[216:217], 1.0 op_sel_hi:[1,0]
	v_pk_add_f32 v[218:219], v[218:219], 1.0 op_sel_hi:[1,0]
	v_pk_add_f32 v[220:221], v[220:221], 1.0 op_sel_hi:[1,0]
	v_pk_add_f32 v[222:223], v[222:223], 1.0 op_sel_hi:[1,0]
	v_rcp_f32_e32 v216, v216
	v_rcp_f32_e32 v217, v217
	v_rcp_f32_e32 v218, v218
	v_rcp_f32_e32 v219, v219
	v_rcp_f32_e32 v220, v220
	v_rcp_f32_e32 v221, v221
	v_rcp_f32_e32 v222, v222
	v_rcp_f32_e32 v223, v223
	v_lshlrev_b32_e32 v242, 16, v158
	v_and_b32_e32 v243, 0xffff0000, v158
	v_lshlrev_b32_e32 v244, 16, v159
	v_and_b32_e32 v245, 0xffff0000, v159
	v_lshlrev_b32_e32 v246, 16, v160
	v_and_b32_e32 v247, 0xffff0000, v160
	v_lshlrev_b32_e32 v248, 16, v161
	v_and_b32_e32 v249, 0xffff0000, v161
	v_pk_mul_f32 v[242:243], v[242:243], s[86:87] op_sel_hi:[1,0]
	v_pk_mul_f32 v[244:245], v[244:245], s[86:87] op_sel_hi:[1,0]
	v_pk_mul_f32 v[246:247], v[246:247], s[86:87] op_sel_hi:[1,0]
	v_pk_mul_f32 v[248:249], v[248:249], s[86:87] op_sel_hi:[1,0]
	v_exp_f32_e32 v242, v242
	v_exp_f32_e32 v243, v243
	v_exp_f32_e32 v244, v244
	v_exp_f32_e32 v245, v245
	v_exp_f32_e32 v246, v246
	v_exp_f32_e32 v247, v247
	v_exp_f32_e32 v248, v248
	v_exp_f32_e32 v249, v249
	v_pk_add_f32 v[242:243], v[242:243], 1.0 op_sel_hi:[1,0]
	v_pk_add_f32 v[244:245], v[244:245], 1.0 op_sel_hi:[1,0]
	v_pk_add_f32 v[246:247], v[246:247], 1.0 op_sel_hi:[1,0]
	v_pk_add_f32 v[248:249], v[248:249], 1.0 op_sel_hi:[1,0]
	v_pk_mul_f32 v[216:217], v[216:217], v[242:243]
	v_pk_mul_f32 v[218:219], v[218:219], v[244:245]
	v_pk_mul_f32 v[220:221], v[220:221], v[246:247]
	v_pk_mul_f32 v[222:223], v[222:223], v[248:249]
	v_pk_mul_f32 v[86:87], v[86:87], v[216:217]
	v_pk_mul_f32 v[88:89], v[88:89], v[218:219]
	v_pk_mul_f32 v[82:83], v[82:83], v[220:221]
	v_pk_mul_f32 v[84:85], v[84:85], v[222:223]
	s_add_u32 s28, s20, 0x3a8000
	s_addc_u32 s29, s21, 0
	global_load_dwordx4 v[146:149], v253, s[28:29]
	global_load_dwordx4 v[150:153], v254, s[28:29]
	global_load_dwordx4 v[154:157], v253, s[28:29] offset:256
	global_load_dwordx4 v[158:161], v254, s[28:29] offset:256
	s_waitcnt vmcnt(12)
	v_lshlrev_b32_e32 v216, 16, v162
	v_and_b32_e32 v217, 0xffff0000, v162
	v_lshlrev_b32_e32 v218, 16, v163
	v_and_b32_e32 v219, 0xffff0000, v163
	v_lshlrev_b32_e32 v220, 16, v164
	v_and_b32_e32 v221, 0xffff0000, v164
	v_lshlrev_b32_e32 v222, 16, v165
	v_and_b32_e32 v223, 0xffff0000, v165
	v_pk_mul_f32 v[216:217], v[216:217], s[86:87] op_sel_hi:[1,0]
	v_pk_mul_f32 v[218:219], v[218:219], s[86:87] op_sel_hi:[1,0]
	v_pk_mul_f32 v[220:221], v[220:221], s[86:87] op_sel_hi:[1,0]
	v_pk_mul_f32 v[222:223], v[222:223], s[86:87] op_sel_hi:[1,0]
	v_exp_f32_e32 v216, v216
	v_exp_f32_e32 v217, v217
	v_exp_f32_e32 v218, v218
	v_exp_f32_e32 v219, v219
	v_exp_f32_e32 v220, v220
	v_exp_f32_e32 v221, v221
	v_exp_f32_e32 v222, v222
	v_exp_f32_e32 v223, v223
	v_pk_add_f32 v[216:217], v[216:217], 1.0 op_sel_hi:[1,0]
	v_pk_add_f32 v[218:219], v[218:219], 1.0 op_sel_hi:[1,0]
	v_pk_add_f32 v[220:221], v[220:221], 1.0 op_sel_hi:[1,0]
	v_pk_add_f32 v[222:223], v[222:223], 1.0 op_sel_hi:[1,0]
	v_rcp_f32_e32 v216, v216
	v_rcp_f32_e32 v217, v217
	v_rcp_f32_e32 v218, v218
	v_rcp_f32_e32 v219, v219
	v_rcp_f32_e32 v220, v220
	v_rcp_f32_e32 v221, v221
	v_rcp_f32_e32 v222, v222
	v_rcp_f32_e32 v223, v223
	v_lshlrev_b32_e32 v242, 16, v166
	v_and_b32_e32 v243, 0xffff0000, v166
	v_lshlrev_b32_e32 v244, 16, v167
	v_and_b32_e32 v245, 0xffff0000, v167
	v_lshlrev_b32_e32 v246, 16, v168
	v_and_b32_e32 v247, 0xffff0000, v168
	v_lshlrev_b32_e32 v248, 16, v169
	v_and_b32_e32 v249, 0xffff0000, v169
	v_pk_mul_f32 v[242:243], v[242:243], s[86:87] op_sel_hi:[1,0]
	v_pk_mul_f32 v[244:245], v[244:245], s[86:87] op_sel_hi:[1,0]
	v_pk_mul_f32 v[246:247], v[246:247], s[86:87] op_sel_hi:[1,0]
	v_pk_mul_f32 v[248:249], v[248:249], s[86:87] op_sel_hi:[1,0]
	v_exp_f32_e32 v242, v242
	v_exp_f32_e32 v243, v243
	v_exp_f32_e32 v244, v244
	v_exp_f32_e32 v245, v245
	v_exp_f32_e32 v246, v246
	v_exp_f32_e32 v247, v247
	v_exp_f32_e32 v248, v248
	v_exp_f32_e32 v249, v249
	v_pk_add_f32 v[242:243], v[242:243], 1.0 op_sel_hi:[1,0]
	v_pk_add_f32 v[244:245], v[244:245], 1.0 op_sel_hi:[1,0]
	v_pk_add_f32 v[246:247], v[246:247], 1.0 op_sel_hi:[1,0]
	v_pk_add_f32 v[248:249], v[248:249], 1.0 op_sel_hi:[1,0]
	v_pk_mul_f32 v[216:217], v[216:217], v[242:243]
	v_pk_mul_f32 v[218:219], v[218:219], v[244:245]
	v_pk_mul_f32 v[220:221], v[220:221], v[246:247]
	v_pk_mul_f32 v[222:223], v[222:223], v[248:249]
	v_pk_mul_f32 v[110:111], v[110:111], v[216:217]
	v_pk_mul_f32 v[112:113], v[112:113], v[218:219]
	v_pk_mul_f32 v[106:107], v[106:107], v[220:221]
	v_pk_mul_f32 v[108:109], v[108:109], v[222:223]
	v_lshlrev_b32_e32 v216, 16, v170
	v_and_b32_e32 v217, 0xffff0000, v170
	v_lshlrev_b32_e32 v218, 16, v171
	v_and_b32_e32 v219, 0xffff0000, v171
	v_lshlrev_b32_e32 v220, 16, v172
	v_and_b32_e32 v221, 0xffff0000, v172
	v_lshlrev_b32_e32 v222, 16, v173
	v_and_b32_e32 v223, 0xffff0000, v173
	v_pk_mul_f32 v[216:217], v[216:217], s[86:87] op_sel_hi:[1,0]
	v_pk_mul_f32 v[218:219], v[218:219], s[86:87] op_sel_hi:[1,0]
	v_pk_mul_f32 v[220:221], v[220:221], s[86:87] op_sel_hi:[1,0]
	v_pk_mul_f32 v[222:223], v[222:223], s[86:87] op_sel_hi:[1,0]
	v_exp_f32_e32 v216, v216
	v_exp_f32_e32 v217, v217
	v_exp_f32_e32 v218, v218
	v_exp_f32_e32 v219, v219
	v_exp_f32_e32 v220, v220
	v_exp_f32_e32 v221, v221
	v_exp_f32_e32 v222, v222
	v_exp_f32_e32 v223, v223
	v_pk_add_f32 v[216:217], v[216:217], 1.0 op_sel_hi:[1,0]
	v_pk_add_f32 v[218:219], v[218:219], 1.0 op_sel_hi:[1,0]
	v_pk_add_f32 v[220:221], v[220:221], 1.0 op_sel_hi:[1,0]
	v_pk_add_f32 v[222:223], v[222:223], 1.0 op_sel_hi:[1,0]
	v_rcp_f32_e32 v216, v216
	v_rcp_f32_e32 v217, v217
	v_rcp_f32_e32 v218, v218
	v_rcp_f32_e32 v219, v219
	v_rcp_f32_e32 v220, v220
	v_rcp_f32_e32 v221, v221
	v_rcp_f32_e32 v222, v222
	v_rcp_f32_e32 v223, v223
	v_lshlrev_b32_e32 v242, 16, v174
	v_and_b32_e32 v243, 0xffff0000, v174
	v_lshlrev_b32_e32 v244, 16, v175
	v_and_b32_e32 v245, 0xffff0000, v175
	v_lshlrev_b32_e32 v246, 16, v176
	v_and_b32_e32 v247, 0xffff0000, v176
	v_lshlrev_b32_e32 v248, 16, v177
	v_and_b32_e32 v249, 0xffff0000, v177
	v_pk_mul_f32 v[242:243], v[242:243], s[86:87] op_sel_hi:[1,0]
	v_pk_mul_f32 v[244:245], v[244:245], s[86:87] op_sel_hi:[1,0]
	v_pk_mul_f32 v[246:247], v[246:247], s[86:87] op_sel_hi:[1,0]
	v_pk_mul_f32 v[248:249], v[248:249], s[86:87] op_sel_hi:[1,0]
	v_exp_f32_e32 v242, v242
	v_exp_f32_e32 v243, v243
	v_exp_f32_e32 v244, v244
	v_exp_f32_e32 v245, v245
	v_exp_f32_e32 v246, v246
	v_exp_f32_e32 v247, v247
	v_exp_f32_e32 v248, v248
	v_exp_f32_e32 v249, v249
	v_pk_add_f32 v[242:243], v[242:243], 1.0 op_sel_hi:[1,0]
	v_pk_add_f32 v[244:245], v[244:245], 1.0 op_sel_hi:[1,0]
	v_pk_add_f32 v[246:247], v[246:247], 1.0 op_sel_hi:[1,0]
	v_pk_add_f32 v[248:249], v[248:249], 1.0 op_sel_hi:[1,0]
	v_pk_mul_f32 v[216:217], v[216:217], v[242:243]
	v_pk_mul_f32 v[218:219], v[218:219], v[244:245]
	v_pk_mul_f32 v[220:221], v[220:221], v[246:247]
	v_pk_mul_f32 v[222:223], v[222:223], v[248:249]
	v_pk_mul_f32 v[78:79], v[78:79], v[216:217]
	v_pk_mul_f32 v[80:81], v[80:81], v[218:219]
	v_pk_mul_f32 v[74:75], v[74:75], v[220:221]
	v_pk_mul_f32 v[76:77], v[76:77], v[222:223]
	s_add_u32 s28, s20, 0x410000
	s_addc_u32 s29, s21, 0
	global_load_dwordx4 v[162:165], v253, s[28:29]
	global_load_dwordx4 v[166:169], v254, s[28:29]
	global_load_dwordx4 v[170:173], v253, s[28:29] offset:256
	global_load_dwordx4 v[174:177], v254, s[28:29] offset:256
	s_waitcnt vmcnt(12)
	v_lshlrev_b32_e32 v216, 16, v178
	v_and_b32_e32 v217, 0xffff0000, v178
	v_lshlrev_b32_e32 v218, 16, v179
	v_and_b32_e32 v219, 0xffff0000, v179
	v_lshlrev_b32_e32 v220, 16, v180
	v_and_b32_e32 v221, 0xffff0000, v180
	v_lshlrev_b32_e32 v222, 16, v181
	v_and_b32_e32 v223, 0xffff0000, v181
	v_pk_mul_f32 v[216:217], v[216:217], s[86:87] op_sel_hi:[1,0]
	v_pk_mul_f32 v[218:219], v[218:219], s[86:87] op_sel_hi:[1,0]
	v_pk_mul_f32 v[220:221], v[220:221], s[86:87] op_sel_hi:[1,0]
	v_pk_mul_f32 v[222:223], v[222:223], s[86:87] op_sel_hi:[1,0]
	v_exp_f32_e32 v216, v216
	v_exp_f32_e32 v217, v217
	v_exp_f32_e32 v218, v218
	v_exp_f32_e32 v219, v219
	v_exp_f32_e32 v220, v220
	v_exp_f32_e32 v221, v221
	v_exp_f32_e32 v222, v222
	v_exp_f32_e32 v223, v223
	v_pk_add_f32 v[216:217], v[216:217], 1.0 op_sel_hi:[1,0]
	v_pk_add_f32 v[218:219], v[218:219], 1.0 op_sel_hi:[1,0]
	v_pk_add_f32 v[220:221], v[220:221], 1.0 op_sel_hi:[1,0]
	v_pk_add_f32 v[222:223], v[222:223], 1.0 op_sel_hi:[1,0]
	v_rcp_f32_e32 v216, v216
	v_rcp_f32_e32 v217, v217
	v_rcp_f32_e32 v218, v218
	v_rcp_f32_e32 v219, v219
	v_rcp_f32_e32 v220, v220
	v_rcp_f32_e32 v221, v221
	v_rcp_f32_e32 v222, v222
	v_rcp_f32_e32 v223, v223
	v_lshlrev_b32_e32 v242, 16, v182
	v_and_b32_e32 v243, 0xffff0000, v182
	v_lshlrev_b32_e32 v244, 16, v183
	v_and_b32_e32 v245, 0xffff0000, v183
	v_lshlrev_b32_e32 v246, 16, v184
	v_and_b32_e32 v247, 0xffff0000, v184
	v_lshlrev_b32_e32 v248, 16, v185
	v_and_b32_e32 v249, 0xffff0000, v185
	v_pk_mul_f32 v[242:243], v[242:243], s[86:87] op_sel_hi:[1,0]
	v_pk_mul_f32 v[244:245], v[244:245], s[86:87] op_sel_hi:[1,0]
	v_pk_mul_f32 v[246:247], v[246:247], s[86:87] op_sel_hi:[1,0]
	v_pk_mul_f32 v[248:249], v[248:249], s[86:87] op_sel_hi:[1,0]
	v_exp_f32_e32 v242, v242
	v_exp_f32_e32 v243, v243
	v_exp_f32_e32 v244, v244
	v_exp_f32_e32 v245, v245
	v_exp_f32_e32 v246, v246
	v_exp_f32_e32 v247, v247
	v_exp_f32_e32 v248, v248
	v_exp_f32_e32 v249, v249
	v_pk_add_f32 v[242:243], v[242:243], 1.0 op_sel_hi:[1,0]
	v_pk_add_f32 v[244:245], v[244:245], 1.0 op_sel_hi:[1,0]
	v_pk_add_f32 v[246:247], v[246:247], 1.0 op_sel_hi:[1,0]
	v_pk_add_f32 v[248:249], v[248:249], 1.0 op_sel_hi:[1,0]
	v_pk_mul_f32 v[216:217], v[216:217], v[242:243]
	v_pk_mul_f32 v[218:219], v[218:219], v[244:245]
	v_pk_mul_f32 v[220:221], v[220:221], v[246:247]
	v_pk_mul_f32 v[222:223], v[222:223], v[248:249]
	v_pk_mul_f32 v[102:103], v[102:103], v[216:217]
	v_pk_mul_f32 v[104:105], v[104:105], v[218:219]
	v_pk_mul_f32 v[98:99], v[98:99], v[220:221]
	v_pk_mul_f32 v[100:101], v[100:101], v[222:223]
	v_lshlrev_b32_e32 v216, 16, v186
	v_and_b32_e32 v217, 0xffff0000, v186
	v_lshlrev_b32_e32 v218, 16, v187
	v_and_b32_e32 v219, 0xffff0000, v187
	v_lshlrev_b32_e32 v220, 16, v188
	v_and_b32_e32 v221, 0xffff0000, v188
	v_lshlrev_b32_e32 v222, 16, v189
	v_and_b32_e32 v223, 0xffff0000, v189
	v_pk_mul_f32 v[216:217], v[216:217], s[86:87] op_sel_hi:[1,0]
	v_pk_mul_f32 v[218:219], v[218:219], s[86:87] op_sel_hi:[1,0]
	v_pk_mul_f32 v[220:221], v[220:221], s[86:87] op_sel_hi:[1,0]
	v_pk_mul_f32 v[222:223], v[222:223], s[86:87] op_sel_hi:[1,0]
	v_exp_f32_e32 v216, v216
	v_exp_f32_e32 v217, v217
	v_exp_f32_e32 v218, v218
	v_exp_f32_e32 v219, v219
	v_exp_f32_e32 v220, v220
	v_exp_f32_e32 v221, v221
	v_exp_f32_e32 v222, v222
	v_exp_f32_e32 v223, v223
	v_pk_add_f32 v[216:217], v[216:217], 1.0 op_sel_hi:[1,0]
	v_pk_add_f32 v[218:219], v[218:219], 1.0 op_sel_hi:[1,0]
	v_pk_add_f32 v[220:221], v[220:221], 1.0 op_sel_hi:[1,0]
	v_pk_add_f32 v[222:223], v[222:223], 1.0 op_sel_hi:[1,0]
	v_rcp_f32_e32 v216, v216
	v_rcp_f32_e32 v217, v217
	v_rcp_f32_e32 v218, v218
	v_rcp_f32_e32 v219, v219
	v_rcp_f32_e32 v220, v220
	v_rcp_f32_e32 v221, v221
	v_rcp_f32_e32 v222, v222
	v_rcp_f32_e32 v223, v223
	v_lshlrev_b32_e32 v242, 16, v190
	v_and_b32_e32 v243, 0xffff0000, v190
	v_lshlrev_b32_e32 v244, 16, v191
	v_and_b32_e32 v245, 0xffff0000, v191
	v_lshlrev_b32_e32 v246, 16, v192
	v_and_b32_e32 v247, 0xffff0000, v192
	v_lshlrev_b32_e32 v248, 16, v193
	v_and_b32_e32 v249, 0xffff0000, v193
	v_pk_mul_f32 v[242:243], v[242:243], s[86:87] op_sel_hi:[1,0]
	v_pk_mul_f32 v[244:245], v[244:245], s[86:87] op_sel_hi:[1,0]
	v_pk_mul_f32 v[246:247], v[246:247], s[86:87] op_sel_hi:[1,0]
	v_pk_mul_f32 v[248:249], v[248:249], s[86:87] op_sel_hi:[1,0]
	v_exp_f32_e32 v242, v242
	v_exp_f32_e32 v243, v243
	v_exp_f32_e32 v244, v244
	v_exp_f32_e32 v245, v245
	v_exp_f32_e32 v246, v246
	v_exp_f32_e32 v247, v247
	v_exp_f32_e32 v248, v248
	v_exp_f32_e32 v249, v249
	v_pk_add_f32 v[242:243], v[242:243], 1.0 op_sel_hi:[1,0]
	v_pk_add_f32 v[244:245], v[244:245], 1.0 op_sel_hi:[1,0]
	v_pk_add_f32 v[246:247], v[246:247], 1.0 op_sel_hi:[1,0]
	v_pk_add_f32 v[248:249], v[248:249], 1.0 op_sel_hi:[1,0]
	v_pk_mul_f32 v[216:217], v[216:217], v[242:243]
	v_pk_mul_f32 v[218:219], v[218:219], v[244:245]
	v_pk_mul_f32 v[220:221], v[220:221], v[246:247]
	v_pk_mul_f32 v[222:223], v[222:223], v[248:249]
	v_pk_mul_f32 v[70:71], v[70:71], v[216:217]
	v_pk_mul_f32 v[72:73], v[72:73], v[218:219]
	v_pk_mul_f32 v[66:67], v[66:67], v[220:221]
	v_pk_mul_f32 v[68:69], v[68:69], v[222:223]
	s_add_u32 s28, s20, 0x478000
	s_addc_u32 s29, s21, 0
	global_load_dwordx4 v[178:181], v253, s[28:29]
	global_load_dwordx4 v[182:185], v254, s[28:29]
	global_load_dwordx4 v[186:189], v253, s[28:29] offset:256
	global_load_dwordx4 v[190:193], v254, s[28:29] offset:256
	s_waitcnt vmcnt(12)
	v_lshlrev_b32_e32 v216, 16, v130
	v_and_b32_e32 v217, 0xffff0000, v130
	v_lshlrev_b32_e32 v218, 16, v131
	v_and_b32_e32 v219, 0xffff0000, v131
	v_lshlrev_b32_e32 v220, 16, v132
	v_and_b32_e32 v221, 0xffff0000, v132
	v_lshlrev_b32_e32 v222, 16, v133
	v_and_b32_e32 v223, 0xffff0000, v133
	v_pk_mul_f32 v[216:217], v[216:217], s[86:87] op_sel_hi:[1,0]
	v_pk_mul_f32 v[218:219], v[218:219], s[86:87] op_sel_hi:[1,0]
	v_pk_mul_f32 v[220:221], v[220:221], s[86:87] op_sel_hi:[1,0]
	v_pk_mul_f32 v[222:223], v[222:223], s[86:87] op_sel_hi:[1,0]
	v_exp_f32_e32 v216, v216
	v_exp_f32_e32 v217, v217
	v_exp_f32_e32 v218, v218
	v_exp_f32_e32 v219, v219
	v_exp_f32_e32 v220, v220
	v_exp_f32_e32 v221, v221
	v_exp_f32_e32 v222, v222
	v_exp_f32_e32 v223, v223
	v_pk_add_f32 v[216:217], v[216:217], 1.0 op_sel_hi:[1,0]
	v_pk_add_f32 v[218:219], v[218:219], 1.0 op_sel_hi:[1,0]
	v_pk_add_f32 v[220:221], v[220:221], 1.0 op_sel_hi:[1,0]
	v_pk_add_f32 v[222:223], v[222:223], 1.0 op_sel_hi:[1,0]
	v_rcp_f32_e32 v216, v216
	v_rcp_f32_e32 v217, v217
	v_rcp_f32_e32 v218, v218
	v_rcp_f32_e32 v219, v219
	v_rcp_f32_e32 v220, v220
	v_rcp_f32_e32 v221, v221
	v_rcp_f32_e32 v222, v222
	v_rcp_f32_e32 v223, v223
	v_lshlrev_b32_e32 v242, 16, v134
	v_and_b32_e32 v243, 0xffff0000, v134
	v_lshlrev_b32_e32 v244, 16, v135
	v_and_b32_e32 v245, 0xffff0000, v135
	v_lshlrev_b32_e32 v246, 16, v136
	v_and_b32_e32 v247, 0xffff0000, v136
	v_lshlrev_b32_e32 v248, 16, v137
	v_and_b32_e32 v249, 0xffff0000, v137
	v_pk_mul_f32 v[242:243], v[242:243], s[86:87] op_sel_hi:[1,0]
	v_pk_mul_f32 v[244:245], v[244:245], s[86:87] op_sel_hi:[1,0]
	v_pk_mul_f32 v[246:247], v[246:247], s[86:87] op_sel_hi:[1,0]
	v_pk_mul_f32 v[248:249], v[248:249], s[86:87] op_sel_hi:[1,0]
	v_exp_f32_e32 v242, v242
	v_exp_f32_e32 v243, v243
	v_exp_f32_e32 v244, v244
	v_exp_f32_e32 v245, v245
	v_exp_f32_e32 v246, v246
	v_exp_f32_e32 v247, v247
	v_exp_f32_e32 v248, v248
	v_exp_f32_e32 v249, v249
	v_pk_add_f32 v[242:243], v[242:243], 1.0 op_sel_hi:[1,0]
	v_pk_add_f32 v[244:245], v[244:245], 1.0 op_sel_hi:[1,0]
	v_pk_add_f32 v[246:247], v[246:247], 1.0 op_sel_hi:[1,0]
	v_pk_add_f32 v[248:249], v[248:249], 1.0 op_sel_hi:[1,0]
	v_pk_mul_f32 v[216:217], v[216:217], v[242:243]
	v_pk_mul_f32 v[218:219], v[218:219], v[244:245]
	v_pk_mul_f32 v[220:221], v[220:221], v[246:247]
	v_pk_mul_f32 v[222:223], v[222:223], v[248:249]
	v_pk_mul_f32 v[62:63], v[62:63], v[216:217]
	v_pk_mul_f32 v[64:65], v[64:65], v[218:219]
	v_pk_mul_f32 v[58:59], v[58:59], v[220:221]
	v_pk_mul_f32 v[60:61], v[60:61], v[222:223]
	v_lshlrev_b32_e32 v216, 16, v138
	v_and_b32_e32 v217, 0xffff0000, v138
	v_lshlrev_b32_e32 v218, 16, v139
	v_and_b32_e32 v219, 0xffff0000, v139
	v_lshlrev_b32_e32 v220, 16, v140
	v_and_b32_e32 v221, 0xffff0000, v140
	v_lshlrev_b32_e32 v222, 16, v141
	v_and_b32_e32 v223, 0xffff0000, v141
	v_pk_mul_f32 v[216:217], v[216:217], s[86:87] op_sel_hi:[1,0]
	v_pk_mul_f32 v[218:219], v[218:219], s[86:87] op_sel_hi:[1,0]
	v_pk_mul_f32 v[220:221], v[220:221], s[86:87] op_sel_hi:[1,0]
	v_pk_mul_f32 v[222:223], v[222:223], s[86:87] op_sel_hi:[1,0]
	v_exp_f32_e32 v216, v216
	v_exp_f32_e32 v217, v217
	v_exp_f32_e32 v218, v218
	v_exp_f32_e32 v219, v219
	v_exp_f32_e32 v220, v220
	v_exp_f32_e32 v221, v221
	v_exp_f32_e32 v222, v222
	v_exp_f32_e32 v223, v223
	v_pk_add_f32 v[216:217], v[216:217], 1.0 op_sel_hi:[1,0]
	v_pk_add_f32 v[218:219], v[218:219], 1.0 op_sel_hi:[1,0]
	v_pk_add_f32 v[220:221], v[220:221], 1.0 op_sel_hi:[1,0]
	v_pk_add_f32 v[222:223], v[222:223], 1.0 op_sel_hi:[1,0]
	v_rcp_f32_e32 v216, v216
	v_rcp_f32_e32 v217, v217
	v_rcp_f32_e32 v218, v218
	v_rcp_f32_e32 v219, v219
	v_rcp_f32_e32 v220, v220
	v_rcp_f32_e32 v221, v221
	v_rcp_f32_e32 v222, v222
	v_rcp_f32_e32 v223, v223
	v_lshlrev_b32_e32 v242, 16, v142
	v_and_b32_e32 v243, 0xffff0000, v142
	v_lshlrev_b32_e32 v244, 16, v143
	v_and_b32_e32 v245, 0xffff0000, v143
	v_lshlrev_b32_e32 v246, 16, v144
	v_and_b32_e32 v247, 0xffff0000, v144
	v_lshlrev_b32_e32 v248, 16, v145
	v_and_b32_e32 v249, 0xffff0000, v145
	v_pk_mul_f32 v[242:243], v[242:243], s[86:87] op_sel_hi:[1,0]
	v_pk_mul_f32 v[244:245], v[244:245], s[86:87] op_sel_hi:[1,0]
	v_pk_mul_f32 v[246:247], v[246:247], s[86:87] op_sel_hi:[1,0]
	v_pk_mul_f32 v[248:249], v[248:249], s[86:87] op_sel_hi:[1,0]
	v_exp_f32_e32 v242, v242
	v_exp_f32_e32 v243, v243
	v_exp_f32_e32 v244, v244
	v_exp_f32_e32 v245, v245
	v_exp_f32_e32 v246, v246
	v_exp_f32_e32 v247, v247
	v_exp_f32_e32 v248, v248
	v_exp_f32_e32 v249, v249
	v_pk_add_f32 v[242:243], v[242:243], 1.0 op_sel_hi:[1,0]
	v_pk_add_f32 v[244:245], v[244:245], 1.0 op_sel_hi:[1,0]
	v_pk_add_f32 v[246:247], v[246:247], 1.0 op_sel_hi:[1,0]
	v_pk_add_f32 v[248:249], v[248:249], 1.0 op_sel_hi:[1,0]
	v_pk_mul_f32 v[216:217], v[216:217], v[242:243]
	v_pk_mul_f32 v[218:219], v[218:219], v[244:245]
	v_pk_mul_f32 v[220:221], v[220:221], v[246:247]
	v_pk_mul_f32 v[222:223], v[222:223], v[248:249]
	v_pk_mul_f32 v[30:31], v[30:31], v[216:217]
	v_pk_mul_f32 v[32:33], v[32:33], v[218:219]
	v_pk_mul_f32 v[26:27], v[26:27], v[220:221]
	v_pk_mul_f32 v[28:29], v[28:29], v[222:223]
	s_waitcnt vmcnt(8)
	v_lshlrev_b32_e32 v216, 16, v146
	v_and_b32_e32 v217, 0xffff0000, v146
	v_lshlrev_b32_e32 v218, 16, v147
	v_and_b32_e32 v219, 0xffff0000, v147
	v_lshlrev_b32_e32 v220, 16, v148
	v_and_b32_e32 v221, 0xffff0000, v148
	v_lshlrev_b32_e32 v222, 16, v149
	v_and_b32_e32 v223, 0xffff0000, v149
	v_pk_mul_f32 v[216:217], v[216:217], s[86:87] op_sel_hi:[1,0]
	v_pk_mul_f32 v[218:219], v[218:219], s[86:87] op_sel_hi:[1,0]
	v_pk_mul_f32 v[220:221], v[220:221], s[86:87] op_sel_hi:[1,0]
	v_pk_mul_f32 v[222:223], v[222:223], s[86:87] op_sel_hi:[1,0]
	v_exp_f32_e32 v216, v216
	v_exp_f32_e32 v217, v217
	v_exp_f32_e32 v218, v218
	v_exp_f32_e32 v219, v219
	v_exp_f32_e32 v220, v220
	v_exp_f32_e32 v221, v221
	v_exp_f32_e32 v222, v222
	v_exp_f32_e32 v223, v223
	v_pk_add_f32 v[216:217], v[216:217], 1.0 op_sel_hi:[1,0]
	v_pk_add_f32 v[218:219], v[218:219], 1.0 op_sel_hi:[1,0]
	v_pk_add_f32 v[220:221], v[220:221], 1.0 op_sel_hi:[1,0]
	v_pk_add_f32 v[222:223], v[222:223], 1.0 op_sel_hi:[1,0]
	v_rcp_f32_e32 v216, v216
	v_rcp_f32_e32 v217, v217
	v_rcp_f32_e32 v218, v218
	v_rcp_f32_e32 v219, v219
	v_rcp_f32_e32 v220, v220
	v_rcp_f32_e32 v221, v221
	v_rcp_f32_e32 v222, v222
	v_rcp_f32_e32 v223, v223
	v_lshlrev_b32_e32 v242, 16, v150
	v_and_b32_e32 v243, 0xffff0000, v150
	v_lshlrev_b32_e32 v244, 16, v151
	v_and_b32_e32 v245, 0xffff0000, v151
	v_lshlrev_b32_e32 v246, 16, v152
	v_and_b32_e32 v247, 0xffff0000, v152
	v_lshlrev_b32_e32 v248, 16, v153
	v_and_b32_e32 v249, 0xffff0000, v153
	v_pk_mul_f32 v[242:243], v[242:243], s[86:87] op_sel_hi:[1,0]
	v_pk_mul_f32 v[244:245], v[244:245], s[86:87] op_sel_hi:[1,0]
	v_pk_mul_f32 v[246:247], v[246:247], s[86:87] op_sel_hi:[1,0]
	v_pk_mul_f32 v[248:249], v[248:249], s[86:87] op_sel_hi:[1,0]
	v_exp_f32_e32 v242, v242
	v_exp_f32_e32 v243, v243
	v_exp_f32_e32 v244, v244
	v_exp_f32_e32 v245, v245
	v_exp_f32_e32 v246, v246
	v_exp_f32_e32 v247, v247
	v_exp_f32_e32 v248, v248
	v_exp_f32_e32 v249, v249
	v_pk_add_f32 v[242:243], v[242:243], 1.0 op_sel_hi:[1,0]
	v_pk_add_f32 v[244:245], v[244:245], 1.0 op_sel_hi:[1,0]
	v_pk_add_f32 v[246:247], v[246:247], 1.0 op_sel_hi:[1,0]
	v_pk_add_f32 v[248:249], v[248:249], 1.0 op_sel_hi:[1,0]
	v_pk_mul_f32 v[216:217], v[216:217], v[242:243]
	v_pk_mul_f32 v[218:219], v[218:219], v[244:245]
	v_pk_mul_f32 v[220:221], v[220:221], v[246:247]
	v_pk_mul_f32 v[222:223], v[222:223], v[248:249]
	v_pk_mul_f32 v[54:55], v[54:55], v[216:217]
	v_pk_mul_f32 v[56:57], v[56:57], v[218:219]
	v_pk_mul_f32 v[50:51], v[50:51], v[220:221]
	v_pk_mul_f32 v[52:53], v[52:53], v[222:223]
	v_lshlrev_b32_e32 v216, 16, v154
	v_and_b32_e32 v217, 0xffff0000, v154
	v_lshlrev_b32_e32 v218, 16, v155
	v_and_b32_e32 v219, 0xffff0000, v155
	v_lshlrev_b32_e32 v220, 16, v156
	v_and_b32_e32 v221, 0xffff0000, v156
	v_lshlrev_b32_e32 v222, 16, v157
	v_and_b32_e32 v223, 0xffff0000, v157
	v_pk_mul_f32 v[216:217], v[216:217], s[86:87] op_sel_hi:[1,0]
	v_pk_mul_f32 v[218:219], v[218:219], s[86:87] op_sel_hi:[1,0]
	v_pk_mul_f32 v[220:221], v[220:221], s[86:87] op_sel_hi:[1,0]
	v_pk_mul_f32 v[222:223], v[222:223], s[86:87] op_sel_hi:[1,0]
	v_exp_f32_e32 v216, v216
	v_exp_f32_e32 v217, v217
	v_exp_f32_e32 v218, v218
	v_exp_f32_e32 v219, v219
	v_exp_f32_e32 v220, v220
	v_exp_f32_e32 v221, v221
	v_exp_f32_e32 v222, v222
	v_exp_f32_e32 v223, v223
	v_pk_add_f32 v[216:217], v[216:217], 1.0 op_sel_hi:[1,0]
	v_pk_add_f32 v[218:219], v[218:219], 1.0 op_sel_hi:[1,0]
	v_pk_add_f32 v[220:221], v[220:221], 1.0 op_sel_hi:[1,0]
	v_pk_add_f32 v[222:223], v[222:223], 1.0 op_sel_hi:[1,0]
	v_rcp_f32_e32 v216, v216
	v_rcp_f32_e32 v217, v217
	v_rcp_f32_e32 v218, v218
	v_rcp_f32_e32 v219, v219
	v_rcp_f32_e32 v220, v220
	v_rcp_f32_e32 v221, v221
	v_rcp_f32_e32 v222, v222
	v_rcp_f32_e32 v223, v223
	v_lshlrev_b32_e32 v242, 16, v158
	v_and_b32_e32 v243, 0xffff0000, v158
	v_lshlrev_b32_e32 v244, 16, v159
	v_and_b32_e32 v245, 0xffff0000, v159
	v_lshlrev_b32_e32 v246, 16, v160
	v_and_b32_e32 v247, 0xffff0000, v160
	v_lshlrev_b32_e32 v248, 16, v161
	v_and_b32_e32 v249, 0xffff0000, v161
	v_pk_mul_f32 v[242:243], v[242:243], s[86:87] op_sel_hi:[1,0]
	v_pk_mul_f32 v[244:245], v[244:245], s[86:87] op_sel_hi:[1,0]
	v_pk_mul_f32 v[246:247], v[246:247], s[86:87] op_sel_hi:[1,0]
	v_pk_mul_f32 v[248:249], v[248:249], s[86:87] op_sel_hi:[1,0]
	v_exp_f32_e32 v242, v242
	v_exp_f32_e32 v243, v243
	v_exp_f32_e32 v244, v244
	v_exp_f32_e32 v245, v245
	v_exp_f32_e32 v246, v246
	v_exp_f32_e32 v247, v247
	v_exp_f32_e32 v248, v248
	v_exp_f32_e32 v249, v249
	v_pk_add_f32 v[242:243], v[242:243], 1.0 op_sel_hi:[1,0]
	v_pk_add_f32 v[244:245], v[244:245], 1.0 op_sel_hi:[1,0]
	v_pk_add_f32 v[246:247], v[246:247], 1.0 op_sel_hi:[1,0]
	v_pk_add_f32 v[248:249], v[248:249], 1.0 op_sel_hi:[1,0]
	v_pk_mul_f32 v[216:217], v[216:217], v[242:243]
	v_pk_mul_f32 v[218:219], v[218:219], v[244:245]
	v_pk_mul_f32 v[220:221], v[220:221], v[246:247]
	v_pk_mul_f32 v[222:223], v[222:223], v[248:249]
	v_pk_mul_f32 v[22:23], v[22:23], v[216:217]
	v_pk_mul_f32 v[24:25], v[24:25], v[218:219]
	v_pk_mul_f32 v[18:19], v[18:19], v[220:221]
	v_pk_mul_f32 v[20:21], v[20:21], v[222:223]
	s_waitcnt vmcnt(4)
	v_lshlrev_b32_e32 v216, 16, v162
	v_and_b32_e32 v217, 0xffff0000, v162
	v_lshlrev_b32_e32 v218, 16, v163
	v_and_b32_e32 v219, 0xffff0000, v163
	v_lshlrev_b32_e32 v220, 16, v164
	v_and_b32_e32 v221, 0xffff0000, v164
	v_lshlrev_b32_e32 v222, 16, v165
	v_and_b32_e32 v223, 0xffff0000, v165
	v_pk_mul_f32 v[216:217], v[216:217], s[86:87] op_sel_hi:[1,0]
	v_pk_mul_f32 v[218:219], v[218:219], s[86:87] op_sel_hi:[1,0]
	v_pk_mul_f32 v[220:221], v[220:221], s[86:87] op_sel_hi:[1,0]
	v_pk_mul_f32 v[222:223], v[222:223], s[86:87] op_sel_hi:[1,0]
	v_exp_f32_e32 v216, v216
	v_exp_f32_e32 v217, v217
	v_exp_f32_e32 v218, v218
	v_exp_f32_e32 v219, v219
	v_exp_f32_e32 v220, v220
	v_exp_f32_e32 v221, v221
	v_exp_f32_e32 v222, v222
	v_exp_f32_e32 v223, v223
	v_pk_add_f32 v[216:217], v[216:217], 1.0 op_sel_hi:[1,0]
	v_pk_add_f32 v[218:219], v[218:219], 1.0 op_sel_hi:[1,0]
	v_pk_add_f32 v[220:221], v[220:221], 1.0 op_sel_hi:[1,0]
	v_pk_add_f32 v[222:223], v[222:223], 1.0 op_sel_hi:[1,0]
	v_rcp_f32_e32 v216, v216
	v_rcp_f32_e32 v217, v217
	v_rcp_f32_e32 v218, v218
	v_rcp_f32_e32 v219, v219
	v_rcp_f32_e32 v220, v220
	v_rcp_f32_e32 v221, v221
	v_rcp_f32_e32 v222, v222
	v_rcp_f32_e32 v223, v223
	v_lshlrev_b32_e32 v242, 16, v166
	v_and_b32_e32 v243, 0xffff0000, v166
	v_lshlrev_b32_e32 v244, 16, v167
	v_and_b32_e32 v245, 0xffff0000, v167
	v_lshlrev_b32_e32 v246, 16, v168
	v_and_b32_e32 v247, 0xffff0000, v168
	v_lshlrev_b32_e32 v248, 16, v169
	v_and_b32_e32 v249, 0xffff0000, v169
	v_pk_mul_f32 v[242:243], v[242:243], s[86:87] op_sel_hi:[1,0]
	v_pk_mul_f32 v[244:245], v[244:245], s[86:87] op_sel_hi:[1,0]
	v_pk_mul_f32 v[246:247], v[246:247], s[86:87] op_sel_hi:[1,0]
	v_pk_mul_f32 v[248:249], v[248:249], s[86:87] op_sel_hi:[1,0]
	v_exp_f32_e32 v242, v242
	v_exp_f32_e32 v243, v243
	v_exp_f32_e32 v244, v244
	v_exp_f32_e32 v245, v245
	v_exp_f32_e32 v246, v246
	v_exp_f32_e32 v247, v247
	v_exp_f32_e32 v248, v248
	v_exp_f32_e32 v249, v249
	v_pk_add_f32 v[242:243], v[242:243], 1.0 op_sel_hi:[1,0]
	v_pk_add_f32 v[244:245], v[244:245], 1.0 op_sel_hi:[1,0]
	v_pk_add_f32 v[246:247], v[246:247], 1.0 op_sel_hi:[1,0]
	v_pk_add_f32 v[248:249], v[248:249], 1.0 op_sel_hi:[1,0]
	v_pk_mul_f32 v[216:217], v[216:217], v[242:243]
	v_pk_mul_f32 v[218:219], v[218:219], v[244:245]
	v_pk_mul_f32 v[220:221], v[220:221], v[246:247]
	v_pk_mul_f32 v[222:223], v[222:223], v[248:249]
	v_pk_mul_f32 v[46:47], v[46:47], v[216:217]
	v_pk_mul_f32 v[48:49], v[48:49], v[218:219]
	v_pk_mul_f32 v[42:43], v[42:43], v[220:221]
	v_pk_mul_f32 v[44:45], v[44:45], v[222:223]
	v_lshlrev_b32_e32 v216, 16, v170
	v_and_b32_e32 v217, 0xffff0000, v170
	v_lshlrev_b32_e32 v218, 16, v171
	v_and_b32_e32 v219, 0xffff0000, v171
	v_lshlrev_b32_e32 v220, 16, v172
	v_and_b32_e32 v221, 0xffff0000, v172
	v_lshlrev_b32_e32 v222, 16, v173
	v_and_b32_e32 v223, 0xffff0000, v173
	v_pk_mul_f32 v[216:217], v[216:217], s[86:87] op_sel_hi:[1,0]
	v_pk_mul_f32 v[218:219], v[218:219], s[86:87] op_sel_hi:[1,0]
	v_pk_mul_f32 v[220:221], v[220:221], s[86:87] op_sel_hi:[1,0]
	v_pk_mul_f32 v[222:223], v[222:223], s[86:87] op_sel_hi:[1,0]
	v_exp_f32_e32 v216, v216
	v_exp_f32_e32 v217, v217
	v_exp_f32_e32 v218, v218
	v_exp_f32_e32 v219, v219
	v_exp_f32_e32 v220, v220
	v_exp_f32_e32 v221, v221
	v_exp_f32_e32 v222, v222
	v_exp_f32_e32 v223, v223
	v_pk_add_f32 v[216:217], v[216:217], 1.0 op_sel_hi:[1,0]
	v_pk_add_f32 v[218:219], v[218:219], 1.0 op_sel_hi:[1,0]
	v_pk_add_f32 v[220:221], v[220:221], 1.0 op_sel_hi:[1,0]
	v_pk_add_f32 v[222:223], v[222:223], 1.0 op_sel_hi:[1,0]
	v_rcp_f32_e32 v216, v216
	v_rcp_f32_e32 v217, v217
	v_rcp_f32_e32 v218, v218
	v_rcp_f32_e32 v219, v219
	v_rcp_f32_e32 v220, v220
	v_rcp_f32_e32 v221, v221
	v_rcp_f32_e32 v222, v222
	v_rcp_f32_e32 v223, v223
	v_lshlrev_b32_e32 v242, 16, v174
	v_and_b32_e32 v243, 0xffff0000, v174
	v_lshlrev_b32_e32 v244, 16, v175
	v_and_b32_e32 v245, 0xffff0000, v175
	v_lshlrev_b32_e32 v246, 16, v176
	v_and_b32_e32 v247, 0xffff0000, v176
	v_lshlrev_b32_e32 v248, 16, v177
	v_and_b32_e32 v249, 0xffff0000, v177
	v_pk_mul_f32 v[242:243], v[242:243], s[86:87] op_sel_hi:[1,0]
	v_pk_mul_f32 v[244:245], v[244:245], s[86:87] op_sel_hi:[1,0]
	v_pk_mul_f32 v[246:247], v[246:247], s[86:87] op_sel_hi:[1,0]
	v_pk_mul_f32 v[248:249], v[248:249], s[86:87] op_sel_hi:[1,0]
	v_exp_f32_e32 v242, v242
	v_exp_f32_e32 v243, v243
	v_exp_f32_e32 v244, v244
	v_exp_f32_e32 v245, v245
	v_exp_f32_e32 v246, v246
	v_exp_f32_e32 v247, v247
	v_exp_f32_e32 v248, v248
	v_exp_f32_e32 v249, v249
	v_pk_add_f32 v[242:243], v[242:243], 1.0 op_sel_hi:[1,0]
	v_pk_add_f32 v[244:245], v[244:245], 1.0 op_sel_hi:[1,0]
	v_pk_add_f32 v[246:247], v[246:247], 1.0 op_sel_hi:[1,0]
	v_pk_add_f32 v[248:249], v[248:249], 1.0 op_sel_hi:[1,0]
	v_pk_mul_f32 v[216:217], v[216:217], v[242:243]
	v_pk_mul_f32 v[218:219], v[218:219], v[244:245]
	v_pk_mul_f32 v[220:221], v[220:221], v[246:247]
	v_pk_mul_f32 v[222:223], v[222:223], v[248:249]
	v_pk_mul_f32 v[14:15], v[14:15], v[216:217]
	v_pk_mul_f32 v[16:17], v[16:17], v[218:219]
	v_pk_mul_f32 v[10:11], v[10:11], v[220:221]
	v_pk_mul_f32 v[12:13], v[12:13], v[222:223]
	s_waitcnt vmcnt(0)
	v_lshlrev_b32_e32 v216, 16, v178
	v_and_b32_e32 v217, 0xffff0000, v178
	v_lshlrev_b32_e32 v218, 16, v179
	v_and_b32_e32 v219, 0xffff0000, v179
	v_lshlrev_b32_e32 v220, 16, v180
	v_and_b32_e32 v221, 0xffff0000, v180
	v_lshlrev_b32_e32 v222, 16, v181
	v_and_b32_e32 v223, 0xffff0000, v181
	v_pk_mul_f32 v[216:217], v[216:217], s[86:87] op_sel_hi:[1,0]
	v_pk_mul_f32 v[218:219], v[218:219], s[86:87] op_sel_hi:[1,0]
	v_pk_mul_f32 v[220:221], v[220:221], s[86:87] op_sel_hi:[1,0]
	v_pk_mul_f32 v[222:223], v[222:223], s[86:87] op_sel_hi:[1,0]
	v_exp_f32_e32 v216, v216
	v_exp_f32_e32 v217, v217
	v_exp_f32_e32 v218, v218
	v_exp_f32_e32 v219, v219
	v_exp_f32_e32 v220, v220
	v_exp_f32_e32 v221, v221
	v_exp_f32_e32 v222, v222
	v_exp_f32_e32 v223, v223
	v_pk_add_f32 v[216:217], v[216:217], 1.0 op_sel_hi:[1,0]
	v_pk_add_f32 v[218:219], v[218:219], 1.0 op_sel_hi:[1,0]
	v_pk_add_f32 v[220:221], v[220:221], 1.0 op_sel_hi:[1,0]
	v_pk_add_f32 v[222:223], v[222:223], 1.0 op_sel_hi:[1,0]
	v_rcp_f32_e32 v216, v216
	v_rcp_f32_e32 v217, v217
	v_rcp_f32_e32 v218, v218
	v_rcp_f32_e32 v219, v219
	v_rcp_f32_e32 v220, v220
	v_rcp_f32_e32 v221, v221
	v_rcp_f32_e32 v222, v222
	v_rcp_f32_e32 v223, v223
	v_lshlrev_b32_e32 v242, 16, v182
	v_and_b32_e32 v243, 0xffff0000, v182
	v_lshlrev_b32_e32 v244, 16, v183
	v_and_b32_e32 v245, 0xffff0000, v183
	v_lshlrev_b32_e32 v246, 16, v184
	v_and_b32_e32 v247, 0xffff0000, v184
	v_lshlrev_b32_e32 v248, 16, v185
	v_and_b32_e32 v249, 0xffff0000, v185
	v_pk_mul_f32 v[242:243], v[242:243], s[86:87] op_sel_hi:[1,0]
	v_pk_mul_f32 v[244:245], v[244:245], s[86:87] op_sel_hi:[1,0]
	v_pk_mul_f32 v[246:247], v[246:247], s[86:87] op_sel_hi:[1,0]
	v_pk_mul_f32 v[248:249], v[248:249], s[86:87] op_sel_hi:[1,0]
	v_exp_f32_e32 v242, v242
	v_exp_f32_e32 v243, v243
	v_exp_f32_e32 v244, v244
	v_exp_f32_e32 v245, v245
	v_exp_f32_e32 v246, v246
	v_exp_f32_e32 v247, v247
	v_exp_f32_e32 v248, v248
	v_exp_f32_e32 v249, v249
	v_pk_add_f32 v[242:243], v[242:243], 1.0 op_sel_hi:[1,0]
	v_pk_add_f32 v[244:245], v[244:245], 1.0 op_sel_hi:[1,0]
	v_pk_add_f32 v[246:247], v[246:247], 1.0 op_sel_hi:[1,0]
	v_pk_add_f32 v[248:249], v[248:249], 1.0 op_sel_hi:[1,0]
	v_pk_mul_f32 v[216:217], v[216:217], v[242:243]
	v_pk_mul_f32 v[218:219], v[218:219], v[244:245]
	v_pk_mul_f32 v[220:221], v[220:221], v[246:247]
	v_pk_mul_f32 v[222:223], v[222:223], v[248:249]
	v_pk_mul_f32 v[38:39], v[38:39], v[216:217]
	v_pk_mul_f32 v[40:41], v[40:41], v[218:219]
	v_pk_mul_f32 v[34:35], v[34:35], v[220:221]
	v_pk_mul_f32 v[36:37], v[36:37], v[222:223]
	v_lshlrev_b32_e32 v216, 16, v186
	v_and_b32_e32 v217, 0xffff0000, v186
	v_lshlrev_b32_e32 v218, 16, v187
	v_and_b32_e32 v219, 0xffff0000, v187
	v_lshlrev_b32_e32 v220, 16, v188
	v_and_b32_e32 v221, 0xffff0000, v188
	v_lshlrev_b32_e32 v222, 16, v189
	v_and_b32_e32 v223, 0xffff0000, v189
	v_pk_mul_f32 v[216:217], v[216:217], s[86:87] op_sel_hi:[1,0]
	v_pk_mul_f32 v[218:219], v[218:219], s[86:87] op_sel_hi:[1,0]
	v_pk_mul_f32 v[220:221], v[220:221], s[86:87] op_sel_hi:[1,0]
	v_pk_mul_f32 v[222:223], v[222:223], s[86:87] op_sel_hi:[1,0]
	v_exp_f32_e32 v216, v216
	v_exp_f32_e32 v217, v217
	v_exp_f32_e32 v218, v218
	v_exp_f32_e32 v219, v219
	v_exp_f32_e32 v220, v220
	v_exp_f32_e32 v221, v221
	v_exp_f32_e32 v222, v222
	v_exp_f32_e32 v223, v223
	v_pk_add_f32 v[216:217], v[216:217], 1.0 op_sel_hi:[1,0]
	v_pk_add_f32 v[218:219], v[218:219], 1.0 op_sel_hi:[1,0]
	v_pk_add_f32 v[220:221], v[220:221], 1.0 op_sel_hi:[1,0]
	v_pk_add_f32 v[222:223], v[222:223], 1.0 op_sel_hi:[1,0]
	v_rcp_f32_e32 v216, v216
	v_rcp_f32_e32 v217, v217
	v_rcp_f32_e32 v218, v218
	v_rcp_f32_e32 v219, v219
	v_rcp_f32_e32 v220, v220
	v_rcp_f32_e32 v221, v221
	v_rcp_f32_e32 v222, v222
	v_rcp_f32_e32 v223, v223
	v_lshlrev_b32_e32 v242, 16, v190
	v_and_b32_e32 v243, 0xffff0000, v190
	v_lshlrev_b32_e32 v244, 16, v191
	v_and_b32_e32 v245, 0xffff0000, v191
	v_lshlrev_b32_e32 v246, 16, v192
	v_and_b32_e32 v247, 0xffff0000, v192
	v_lshlrev_b32_e32 v248, 16, v193
	v_and_b32_e32 v249, 0xffff0000, v193
	v_pk_mul_f32 v[242:243], v[242:243], s[86:87] op_sel_hi:[1,0]
	v_pk_mul_f32 v[244:245], v[244:245], s[86:87] op_sel_hi:[1,0]
	v_pk_mul_f32 v[246:247], v[246:247], s[86:87] op_sel_hi:[1,0]
	v_pk_mul_f32 v[248:249], v[248:249], s[86:87] op_sel_hi:[1,0]
	v_exp_f32_e32 v242, v242
	v_exp_f32_e32 v243, v243
	v_exp_f32_e32 v244, v244
	v_exp_f32_e32 v245, v245
	v_exp_f32_e32 v246, v246
	v_exp_f32_e32 v247, v247
	v_exp_f32_e32 v248, v248
	v_exp_f32_e32 v249, v249
	v_pk_add_f32 v[242:243], v[242:243], 1.0 op_sel_hi:[1,0]
	v_pk_add_f32 v[244:245], v[244:245], 1.0 op_sel_hi:[1,0]
	v_pk_add_f32 v[246:247], v[246:247], 1.0 op_sel_hi:[1,0]
	v_pk_add_f32 v[248:249], v[248:249], 1.0 op_sel_hi:[1,0]
	v_pk_mul_f32 v[216:217], v[216:217], v[242:243]
	v_pk_mul_f32 v[218:219], v[218:219], v[244:245]
	v_pk_mul_f32 v[220:221], v[220:221], v[246:247]
	v_pk_mul_f32 v[222:223], v[222:223], v[248:249]
	v_pk_mul_f32 v[6:7], v[6:7], v[216:217]
	v_pk_mul_f32 v[8:9], v[8:9], v[218:219]
	v_pk_mul_f32 v[2:3], v[2:3], v[220:221]
	v_pk_mul_f32 v[4:5], v[4:5], v[222:223]
	s_branch .Lem_done
.Lem_br2:
	global_load_dwordx4 v[130:133], v253, s[20:21]
	global_load_dwordx4 v[138:141], v253, s[20:21] offset:256
	s_add_u32 s28, s20, 0x68000
	s_addc_u32 s29, s21, 0
	global_load_dwordx4 v[146:149], v253, s[28:29]
	global_load_dwordx4 v[154:157], v253, s[28:29] offset:256
	s_add_u32 s28, s20, 0xd0000
	s_addc_u32 s29, s21, 0
	global_load_dwordx4 v[162:165], v253, s[28:29]
	global_load_dwordx4 v[170:173], v253, s[28:29] offset:256
	s_add_u32 s28, s20, 0x138000
	s_addc_u32 s29, s21, 0
	global_load_dwordx4 v[178:181], v253, s[28:29]
	global_load_dwordx4 v[186:189], v253, s[28:29] offset:256
	s_waitcnt vmcnt(6)
	v_lshlrev_b32_e32 v216, 16, v130
	v_and_b32_e32 v217, 0xffff0000, v130
	v_lshlrev_b32_e32 v218, 16, v131
	v_and_b32_e32 v219, 0xffff0000, v131
	v_lshlrev_b32_e32 v220, 16, v132
	v_and_b32_e32 v221, 0xffff0000, v132
	v_lshlrev_b32_e32 v222, 16, v133
	v_and_b32_e32 v223, 0xffff0000, v133
	v_pk_mul_f32 v[216:217], v[216:217], s[86:87] op_sel_hi:[1,0]
	v_pk_mul_f32 v[218:219], v[218:219], s[86:87] op_sel_hi:[1,0]
	v_pk_mul_f32 v[220:221], v[220:221], s[86:87] op_sel_hi:[1,0]
	v_pk_mul_f32 v[222:223], v[222:223], s[86:87] op_sel_hi:[1,0]
	v_exp_f32_e32 v216, v216
	v_exp_f32_e32 v217, v217
	v_exp_f32_e32 v218, v218
	v_exp_f32_e32 v219, v219
	v_exp_f32_e32 v220, v220
	v_exp_f32_e32 v221, v221
	v_exp_f32_e32 v222, v222
	v_exp_f32_e32 v223, v223
	v_pk_add_f32 v[216:217], v[216:217], 1.0 op_sel_hi:[1,0]
	v_pk_add_f32 v[218:219], v[218:219], 1.0 op_sel_hi:[1,0]
	v_pk_add_f32 v[220:221], v[220:221], 1.0 op_sel_hi:[1,0]
	v_pk_add_f32 v[222:223], v[222:223], 1.0 op_sel_hi:[1,0]
	v_rcp_f32_e32 v216, v216
	v_rcp_f32_e32 v217, v217
	v_rcp_f32_e32 v218, v218
	v_rcp_f32_e32 v219, v219
	v_rcp_f32_e32 v220, v220
	v_rcp_f32_e32 v221, v221
	v_rcp_f32_e32 v222, v222
	v_rcp_f32_e32 v223, v223
	s_nop 0
	v_pk_mul_f32 v[126:127], v[126:127], v[216:217]
	v_pk_mul_f32 v[128:129], v[128:129], v[218:219]
	v_pk_mul_f32 v[122:123], v[122:123], v[220:221]
	v_pk_mul_f32 v[124:125], v[124:125], v[222:223]
	v_cvt_pk_bf16_f32 v242, v126, v127
	v_cvt_pk_bf16_f32 v243, v128, v129
	v_cvt_pk_bf16_f32 v244, v122, v123
	v_cvt_pk_bf16_f32 v245, v124, v125
	global_store_dwordx4 v255, v[242:245], s[10:11]
	v_lshlrev_b32_e32 v216, 16, v138
	v_and_b32_e32 v217, 0xffff0000, v138
	v_lshlrev_b32_e32 v218, 16, v139
	v_and_b32_e32 v219, 0xffff0000, v139
	v_lshlrev_b32_e32 v220, 16, v140
	v_and_b32_e32 v221, 0xffff0000, v140
	v_lshlrev_b32_e32 v222, 16, v141
	v_and_b32_e32 v223, 0xffff0000, v141
	v_pk_mul_f32 v[216:217], v[216:217], s[86:87] op_sel_hi:[1,0]
	v_pk_mul_f32 v[218:219], v[218:219], s[86:87] op_sel_hi:[1,0]
	v_pk_mul_f32 v[220:221], v[220:221], s[86:87] op_sel_hi:[1,0]
	v_pk_mul_f32 v[222:223], v[222:223], s[86:87] op_sel_hi:[1,0]
	v_exp_f32_e32 v216, v216
	v_exp_f32_e32 v217, v217
	v_exp_f32_e32 v218, v218
	v_exp_f32_e32 v219, v219
	v_exp_f32_e32 v220, v220
	v_exp_f32_e32 v221, v221
	v_exp_f32_e32 v222, v222
	v_exp_f32_e32 v223, v223
	v_pk_add_f32 v[216:217], v[216:217], 1.0 op_sel_hi:[1,0]
	v_pk_add_f32 v[218:219], v[218:219], 1.0 op_sel_hi:[1,0]
	v_pk_add_f32 v[220:221], v[220:221], 1.0 op_sel_hi:[1,0]
	v_pk_add_f32 v[222:223], v[222:223], 1.0 op_sel_hi:[1,0]
	v_rcp_f32_e32 v216, v216
	v_rcp_f32_e32 v217, v217
	v_rcp_f32_e32 v218, v218
	v_rcp_f32_e32 v219, v219
	v_rcp_f32_e32 v220, v220
	v_rcp_f32_e32 v221, v221
	v_rcp_f32_e32 v222, v222
	v_rcp_f32_e32 v223, v223
	s_nop 0
	v_pk_mul_f32 v[94:95], v[94:95], v[216:217]
	v_pk_mul_f32 v[96:97], v[96:97], v[218:219]
	v_pk_mul_f32 v[90:91], v[90:91], v[220:221]
	v_pk_mul_f32 v[92:93], v[92:93], v[222:223]
	v_cvt_pk_bf16_f32 v242, v94, v95
	v_cvt_pk_bf16_f32 v243, v96, v97
	v_cvt_pk_bf16_f32 v244, v90, v91
	v_cvt_pk_bf16_f32 v245, v92, v93
	global_store_dwordx4 v255, v[242:245], s[10:11] offset:256
	s_add_u32 s28, s20, 0x340000
	s_addc_u32 s29, s21, 0
	global_load_dwordx4 v[130:133], v253, s[28:29]
	global_load_dwordx4 v[138:141], v253, s[28:29] offset:256
	s_waitcnt vmcnt(8)
	s_add_u32 s8, s10, 0x10000
	s_addc_u32 s9, s11, 0
	v_lshlrev_b32_e32 v216, 16, v146
	v_and_b32_e32 v217, 0xffff0000, v146
	v_lshlrev_b32_e32 v218, 16, v147
	v_and_b32_e32 v219, 0xffff0000, v147
	v_lshlrev_b32_e32 v220, 16, v148
	v_and_b32_e32 v221, 0xffff0000, v148
	v_lshlrev_b32_e32 v222, 16, v149
	v_and_b32_e32 v223, 0xffff0000, v149
	v_pk_mul_f32 v[216:217], v[216:217], s[86:87] op_sel_hi:[1,0]
	v_pk_mul_f32 v[218:219], v[218:219], s[86:87] op_sel_hi:[1,0]
	v_pk_mul_f32 v[220:221], v[220:221], s[86:87] op_sel_hi:[1,0]
	v_pk_mul_f32 v[222:223], v[222:223], s[86:87] op_sel_hi:[1,0]
	v_exp_f32_e32 v216, v216
	v_exp_f32_e32 v217, v217
	v_exp_f32_e32 v218, v218
	v_exp_f32_e32 v219, v219
	v_exp_f32_e32 v220, v220
	v_exp_f32_e32 v221, v221
	v_exp_f32_e32 v222, v222
	v_exp_f32_e32 v223, v223
	v_pk_add_f32 v[216:217], v[216:217], 1.0 op_sel_hi:[1,0]
	v_pk_add_f32 v[218:219], v[218:219], 1.0 op_sel_hi:[1,0]
	v_pk_add_f32 v[220:221], v[220:221], 1.0 op_sel_hi:[1,0]
	v_pk_add_f32 v[222:223], v[222:223], 1.0 op_sel_hi:[1,0]
	v_rcp_f32_e32 v216, v216
	v_rcp_f32_e32 v217, v217
	v_rcp_f32_e32 v218, v218
	v_rcp_f32_e32 v219, v219
	v_rcp_f32_e32 v220, v220
	v_rcp_f32_e32 v221, v221
	v_rcp_f32_e32 v222, v222
	v_rcp_f32_e32 v223, v223
	s_nop 0
	v_pk_mul_f32 v[118:119], v[118:119], v[216:217]
	v_pk_mul_f32 v[120:121], v[120:121], v[218:219]
	v_pk_mul_f32 v[114:115], v[114:115], v[220:221]
	v_pk_mul_f32 v[116:117], v[116:117], v[222:223]
	v_cvt_pk_bf16_f32 v242, v118, v119
	v_cvt_pk_bf16_f32 v243, v120, v121
	v_cvt_pk_bf16_f32 v244, v114, v115
	v_cvt_pk_bf16_f32 v245, v116, v117
	global_store_dwordx4 v255, v[242:245], s[8:9]
	v_lshlrev_b32_e32 v216, 16, v154
	v_and_b32_e32 v217, 0xffff0000, v154
	v_lshlrev_b32_e32 v218, 16, v155
	v_and_b32_e32 v219, 0xffff0000, v155
	v_lshlrev_b32_e32 v220, 16, v156
	v_and_b32_e32 v221, 0xffff0000, v156
	v_lshlrev_b32_e32 v222, 16, v157
	v_and_b32_e32 v223, 0xffff0000, v157
	v_pk_mul_f32 v[216:217], v[216:217], s[86:87] op_sel_hi:[1,0]
	v_pk_mul_f32 v[218:219], v[218:219], s[86:87] op_sel_hi:[1,0]
	v_pk_mul_f32 v[220:221], v[220:221], s[86:87] op_sel_hi:[1,0]
	v_pk_mul_f32 v[222:223], v[222:223], s[86:87] op_sel_hi:[1,0]
	v_exp_f32_e32 v216, v216
	v_exp_f32_e32 v217, v217
	v_exp_f32_e32 v218, v218
	v_exp_f32_e32 v219, v219
	v_exp_f32_e32 v220, v220
	v_exp_f32_e32 v221, v221
	v_exp_f32_e32 v222, v222
	v_exp_f32_e32 v223, v223
	v_pk_add_f32 v[216:217], v[216:217], 1.0 op_sel_hi:[1,0]
	v_pk_add_f32 v[218:219], v[218:219], 1.0 op_sel_hi:[1,0]
	v_pk_add_f32 v[220:221], v[220:221], 1.0 op_sel_hi:[1,0]
	v_pk_add_f32 v[222:223], v[222:223], 1.0 op_sel_hi:[1,0]
	v_rcp_f32_e32 v216, v216
	v_rcp_f32_e32 v217, v217
	v_rcp_f32_e32 v218, v218
	v_rcp_f32_e32 v219, v219
	v_rcp_f32_e32 v220, v220
	v_rcp_f32_e32 v221, v221
	v_rcp_f32_e32 v222, v222
	v_rcp_f32_e32 v223, v223
	s_nop 0
	v_pk_mul_f32 v[86:87], v[86:87], v[216:217]
	v_pk_mul_f32 v[88:89], v[88:89], v[218:219]
	v_pk_mul_f32 v[82:83], v[82:83], v[220:221]
	v_pk_mul_f32 v[84:85], v[84:85], v[222:223]
	v_cvt_pk_bf16_f32 v242, v86, v87
	v_cvt_pk_bf16_f32 v243, v88, v89
	v_cvt_pk_bf16_f32 v244, v82, v83
	v_cvt_pk_bf16_f32 v245, v84, v85
	global_store_dwordx4 v255, v[242:245], s[8:9] offset:256
	s_add_u32 s28, s20, 0x3a8000
	s_addc_u32 s29, s21, 0
	global_load_dwordx4 v[146:149], v253, s[28:29]
	global_load_dwordx4 v[154:157], v253, s[28:29] offset:256
	s_waitcnt vmcnt(10)
	s_add_u32 s8, s10, 0x20000
	s_addc_u32 s9, s11, 0
	v_lshlrev_b32_e32 v216, 16, v162
	v_and_b32_e32 v217, 0xffff0000, v162
	v_lshlrev_b32_e32 v218, 16, v163
	v_and_b32_e32 v219, 0xffff0000, v163
	v_lshlrev_b32_e32 v220, 16, v164
	v_and_b32_e32 v221, 0xffff0000, v164
	v_lshlrev_b32_e32 v222, 16, v165
	v_and_b32_e32 v223, 0xffff0000, v165
	v_pk_mul_f32 v[216:217], v[216:217], s[86:87] op_sel_hi:[1,0]
	v_pk_mul_f32 v[218:219], v[218:219], s[86:87] op_sel_hi:[1,0]
	v_pk_mul_f32 v[220:221], v[220:221], s[86:87] op_sel_hi:[1,0]
	v_pk_mul_f32 v[222:223], v[222:223], s[86:87] op_sel_hi:[1,0]
	v_exp_f32_e32 v216, v216
	v_exp_f32_e32 v217, v217
	v_exp_f32_e32 v218, v218
	v_exp_f32_e32 v219, v219
	v_exp_f32_e32 v220, v220
	v_exp_f32_e32 v221, v221
	v_exp_f32_e32 v222, v222
	v_exp_f32_e32 v223, v223
	v_pk_add_f32 v[216:217], v[216:217], 1.0 op_sel_hi:[1,0]
	v_pk_add_f32 v[218:219], v[218:219], 1.0 op_sel_hi:[1,0]
	v_pk_add_f32 v[220:221], v[220:221], 1.0 op_sel_hi:[1,0]
	v_pk_add_f32 v[222:223], v[222:223], 1.0 op_sel_hi:[1,0]
	v_rcp_f32_e32 v216, v216
	v_rcp_f32_e32 v217, v217
	v_rcp_f32_e32 v218, v218
	v_rcp_f32_e32 v219, v219
	v_rcp_f32_e32 v220, v220
	v_rcp_f32_e32 v221, v221
	v_rcp_f32_e32 v222, v222
	v_rcp_f32_e32 v223, v223
	s_nop 0
	v_pk_mul_f32 v[110:111], v[110:111], v[216:217]
	v_pk_mul_f32 v[112:113], v[112:113], v[218:219]
	v_pk_mul_f32 v[106:107], v[106:107], v[220:221]
	v_pk_mul_f32 v[108:109], v[108:109], v[222:223]
	v_cvt_pk_bf16_f32 v242, v110, v111
	v_cvt_pk_bf16_f32 v243, v112, v113
	v_cvt_pk_bf16_f32 v244, v106, v107
	v_cvt_pk_bf16_f32 v245, v108, v109
	global_store_dwordx4 v255, v[242:245], s[8:9]
	v_lshlrev_b32_e32 v216, 16, v170
	v_and_b32_e32 v217, 0xffff0000, v170
	v_lshlrev_b32_e32 v218, 16, v171
	v_and_b32_e32 v219, 0xffff0000, v171
	v_lshlrev_b32_e32 v220, 16, v172
	v_and_b32_e32 v221, 0xffff0000, v172
	v_lshlrev_b32_e32 v222, 16, v173
	v_and_b32_e32 v223, 0xffff0000, v173
	v_pk_mul_f32 v[216:217], v[216:217], s[86:87] op_sel_hi:[1,0]
	v_pk_mul_f32 v[218:219], v[218:219], s[86:87] op_sel_hi:[1,0]
	v_pk_mul_f32 v[220:221], v[220:221], s[86:87] op_sel_hi:[1,0]
	v_pk_mul_f32 v[222:223], v[222:223], s[86:87] op_sel_hi:[1,0]
	v_exp_f32_e32 v216, v216
	v_exp_f32_e32 v217, v217
	v_exp_f32_e32 v218, v218
	v_exp_f32_e32 v219, v219
	v_exp_f32_e32 v220, v220
	v_exp_f32_e32 v221, v221
	v_exp_f32_e32 v222, v222
	v_exp_f32_e32 v223, v223
	v_pk_add_f32 v[216:217], v[216:217], 1.0 op_sel_hi:[1,0]
	v_pk_add_f32 v[218:219], v[218:219], 1.0 op_sel_hi:[1,0]
	v_pk_add_f32 v[220:221], v[220:221], 1.0 op_sel_hi:[1,0]
	v_pk_add_f32 v[222:223], v[222:223], 1.0 op_sel_hi:[1,0]
	v_rcp_f32_e32 v216, v216
	v_rcp_f32_e32 v217, v217
	v_rcp_f32_e32 v218, v218
	v_rcp_f32_e32 v219, v219
	v_rcp_f32_e32 v220, v220
	v_rcp_f32_e32 v221, v221
	v_rcp_f32_e32 v222, v222
	v_rcp_f32_e32 v223, v223
	s_nop 0
	v_pk_mul_f32 v[78:79], v[78:79], v[216:217]
	v_pk_mul_f32 v[80:81], v[80:81], v[218:219]
	v_pk_mul_f32 v[74:75], v[74:75], v[220:221]
	v_pk_mul_f32 v[76:77], v[76:77], v[222:223]
	v_cvt_pk_bf16_f32 v242, v78, v79
	v_cvt_pk_bf16_f32 v243, v80, v81
	v_cvt_pk_bf16_f32 v244, v74, v75
	v_cvt_pk_bf16_f32 v245, v76, v77
	global_store_dwordx4 v255, v[242:245], s[8:9] offset:256
	s_add_u32 s28, s20, 0x410000
	s_addc_u32 s29, s21, 0
	global_load_dwordx4 v[162:165], v253, s[28:29]
	global_load_dwordx4 v[170:173], v253, s[28:29] offset:256
	s_waitcnt vmcnt(12)
	s_add_u32 s8, s10, 0x30000
	s_addc_u32 s9, s11, 0
	v_lshlrev_b32_e32 v216, 16, v178
	v_and_b32_e32 v217, 0xffff0000, v178
	v_lshlrev_b32_e32 v218, 16, v179
	v_and_b32_e32 v219, 0xffff0000, v179
	v_lshlrev_b32_e32 v220, 16, v180
	v_and_b32_e32 v221, 0xffff0000, v180
	v_lshlrev_b32_e32 v222, 16, v181
	v_and_b32_e32 v223, 0xffff0000, v181
	v_pk_mul_f32 v[216:217], v[216:217], s[86:87] op_sel_hi:[1,0]
	v_pk_mul_f32 v[218:219], v[218:219], s[86:87] op_sel_hi:[1,0]
	v_pk_mul_f32 v[220:221], v[220:221], s[86:87] op_sel_hi:[1,0]
	v_pk_mul_f32 v[222:223], v[222:223], s[86:87] op_sel_hi:[1,0]
	v_exp_f32_e32 v216, v216
	v_exp_f32_e32 v217, v217
	v_exp_f32_e32 v218, v218
	v_exp_f32_e32 v219, v219
	v_exp_f32_e32 v220, v220
	v_exp_f32_e32 v221, v221
	v_exp_f32_e32 v222, v222
	v_exp_f32_e32 v223, v223
	v_pk_add_f32 v[216:217], v[216:217], 1.0 op_sel_hi:[1,0]
	v_pk_add_f32 v[218:219], v[218:219], 1.0 op_sel_hi:[1,0]
	v_pk_add_f32 v[220:221], v[220:221], 1.0 op_sel_hi:[1,0]
	v_pk_add_f32 v[222:223], v[222:223], 1.0 op_sel_hi:[1,0]
	v_rcp_f32_e32 v216, v216
	v_rcp_f32_e32 v217, v217
	v_rcp_f32_e32 v218, v218
	v_rcp_f32_e32 v219, v219
	v_rcp_f32_e32 v220, v220
	v_rcp_f32_e32 v221, v221
	v_rcp_f32_e32 v222, v222
	v_rcp_f32_e32 v223, v223
	s_nop 0
	v_pk_mul_f32 v[102:103], v[102:103], v[216:217]
	v_pk_mul_f32 v[104:105], v[104:105], v[218:219]
	v_pk_mul_f32 v[98:99], v[98:99], v[220:221]
	v_pk_mul_f32 v[100:101], v[100:101], v[222:223]
	v_cvt_pk_bf16_f32 v242, v102, v103
	v_cvt_pk_bf16_f32 v243, v104, v105
	v_cvt_pk_bf16_f32 v244, v98, v99
	v_cvt_pk_bf16_f32 v245, v100, v101
	global_store_dwordx4 v255, v[242:245], s[8:9]
	v_lshlrev_b32_e32 v216, 16, v186
	v_and_b32_e32 v217, 0xffff0000, v186
	v_lshlrev_b32_e32 v218, 16, v187
	v_and_b32_e32 v219, 0xffff0000, v187
	v_lshlrev_b32_e32 v220, 16, v188
	v_and_b32_e32 v221, 0xffff0000, v188
	v_lshlrev_b32_e32 v222, 16, v189
	v_and_b32_e32 v223, 0xffff0000, v189
	v_pk_mul_f32 v[216:217], v[216:217], s[86:87] op_sel_hi:[1,0]
	v_pk_mul_f32 v[218:219], v[218:219], s[86:87] op_sel_hi:[1,0]
	v_pk_mul_f32 v[220:221], v[220:221], s[86:87] op_sel_hi:[1,0]
	v_pk_mul_f32 v[222:223], v[222:223], s[86:87] op_sel_hi:[1,0]
	v_exp_f32_e32 v216, v216
	v_exp_f32_e32 v217, v217
	v_exp_f32_e32 v218, v218
	v_exp_f32_e32 v219, v219
	v_exp_f32_e32 v220, v220
	v_exp_f32_e32 v221, v221
	v_exp_f32_e32 v222, v222
	v_exp_f32_e32 v223, v223
	v_pk_add_f32 v[216:217], v[216:217], 1.0 op_sel_hi:[1,0]
	v_pk_add_f32 v[218:219], v[218:219], 1.0 op_sel_hi:[1,0]
	v_pk_add_f32 v[220:221], v[220:221], 1.0 op_sel_hi:[1,0]
	v_pk_add_f32 v[222:223], v[222:223], 1.0 op_sel_hi:[1,0]
	v_rcp_f32_e32 v216, v216
	v_rcp_f32_e32 v217, v217
	v_rcp_f32_e32 v218, v218
	v_rcp_f32_e32 v219, v219
	v_rcp_f32_e32 v220, v220
	v_rcp_f32_e32 v221, v221
	v_rcp_f32_e32 v222, v222
	v_rcp_f32_e32 v223, v223
	s_nop 0
	v_pk_mul_f32 v[70:71], v[70:71], v[216:217]
	v_pk_mul_f32 v[72:73], v[72:73], v[218:219]
	v_pk_mul_f32 v[66:67], v[66:67], v[220:221]
	v_pk_mul_f32 v[68:69], v[68:69], v[222:223]
	v_cvt_pk_bf16_f32 v242, v70, v71
	v_cvt_pk_bf16_f32 v243, v72, v73
	v_cvt_pk_bf16_f32 v244, v66, v67
	v_cvt_pk_bf16_f32 v245, v68, v69
	global_store_dwordx4 v255, v[242:245], s[8:9] offset:256
	s_add_u32 s28, s20, 0x478000
	s_addc_u32 s29, s21, 0
	global_load_dwordx4 v[178:181], v253, s[28:29]
	global_load_dwordx4 v[186:189], v253, s[28:29] offset:256
	s_waitcnt vmcnt(12)
	s_add_u32 s8, s10, 0x80000
	s_addc_u32 s9, s11, 0
	v_lshlrev_b32_e32 v216, 16, v130
	v_and_b32_e32 v217, 0xffff0000, v130
	v_lshlrev_b32_e32 v218, 16, v131
	v_and_b32_e32 v219, 0xffff0000, v131
	v_lshlrev_b32_e32 v220, 16, v132
	v_and_b32_e32 v221, 0xffff0000, v132
	v_lshlrev_b32_e32 v222, 16, v133
	v_and_b32_e32 v223, 0xffff0000, v133
	v_pk_mul_f32 v[216:217], v[216:217], s[86:87] op_sel_hi:[1,0]
	v_pk_mul_f32 v[218:219], v[218:219], s[86:87] op_sel_hi:[1,0]
	v_pk_mul_f32 v[220:221], v[220:221], s[86:87] op_sel_hi:[1,0]
	v_pk_mul_f32 v[222:223], v[222:223], s[86:87] op_sel_hi:[1,0]
	v_exp_f32_e32 v216, v216
	v_exp_f32_e32 v217, v217
	v_exp_f32_e32 v218, v218
	v_exp_f32_e32 v219, v219
	v_exp_f32_e32 v220, v220
	v_exp_f32_e32 v221, v221
	v_exp_f32_e32 v222, v222
	v_exp_f32_e32 v223, v223
	v_pk_add_f32 v[216:217], v[216:217], 1.0 op_sel_hi:[1,0]
	v_pk_add_f32 v[218:219], v[218:219], 1.0 op_sel_hi:[1,0]
	v_pk_add_f32 v[220:221], v[220:221], 1.0 op_sel_hi:[1,0]
	v_pk_add_f32 v[222:223], v[222:223], 1.0 op_sel_hi:[1,0]
	v_rcp_f32_e32 v216, v216
	v_rcp_f32_e32 v217, v217
	v_rcp_f32_e32 v218, v218
	v_rcp_f32_e32 v219, v219
	v_rcp_f32_e32 v220, v220
	v_rcp_f32_e32 v221, v221
	v_rcp_f32_e32 v222, v222
	v_rcp_f32_e32 v223, v223
	s_nop 0
	v_pk_mul_f32 v[62:63], v[62:63], v[216:217]
	v_pk_mul_f32 v[64:65], v[64:65], v[218:219]
	v_pk_mul_f32 v[58:59], v[58:59], v[220:221]
	v_pk_mul_f32 v[60:61], v[60:61], v[222:223]
	v_cvt_pk_bf16_f32 v242, v62, v63
	v_cvt_pk_bf16_f32 v243, v64, v65
	v_cvt_pk_bf16_f32 v244, v58, v59
	v_cvt_pk_bf16_f32 v245, v60, v61
	global_store_dwordx4 v255, v[242:245], s[8:9]
	v_lshlrev_b32_e32 v216, 16, v138
	v_and_b32_e32 v217, 0xffff0000, v138
	v_lshlrev_b32_e32 v218, 16, v139
	v_and_b32_e32 v219, 0xffff0000, v139
	v_lshlrev_b32_e32 v220, 16, v140
	v_and_b32_e32 v221, 0xffff0000, v140
	v_lshlrev_b32_e32 v222, 16, v141
	v_and_b32_e32 v223, 0xffff0000, v141
	v_pk_mul_f32 v[216:217], v[216:217], s[86:87] op_sel_hi:[1,0]
	v_pk_mul_f32 v[218:219], v[218:219], s[86:87] op_sel_hi:[1,0]
	v_pk_mul_f32 v[220:221], v[220:221], s[86:87] op_sel_hi:[1,0]
	v_pk_mul_f32 v[222:223], v[222:223], s[86:87] op_sel_hi:[1,0]
	v_exp_f32_e32 v216, v216
	v_exp_f32_e32 v217, v217
	v_exp_f32_e32 v218, v218
	v_exp_f32_e32 v219, v219
	v_exp_f32_e32 v220, v220
	v_exp_f32_e32 v221, v221
	v_exp_f32_e32 v222, v222
	v_exp_f32_e32 v223, v223
	v_pk_add_f32 v[216:217], v[216:217], 1.0 op_sel_hi:[1,0]
	v_pk_add_f32 v[218:219], v[218:219], 1.0 op_sel_hi:[1,0]
	v_pk_add_f32 v[220:221], v[220:221], 1.0 op_sel_hi:[1,0]
	v_pk_add_f32 v[222:223], v[222:223], 1.0 op_sel_hi:[1,0]
	v_rcp_f32_e32 v216, v216
	v_rcp_f32_e32 v217, v217
	v_rcp_f32_e32 v218, v218
	v_rcp_f32_e32 v219, v219
	v_rcp_f32_e32 v220, v220
	v_rcp_f32_e32 v221, v221
	v_rcp_f32_e32 v222, v222
	v_rcp_f32_e32 v223, v223
	s_nop 0
	v_pk_mul_f32 v[30:31], v[30:31], v[216:217]
	v_pk_mul_f32 v[32:33], v[32:33], v[218:219]
	v_pk_mul_f32 v[26:27], v[26:27], v[220:221]
	v_pk_mul_f32 v[28:29], v[28:29], v[222:223]
	v_cvt_pk_bf16_f32 v242, v30, v31
	v_cvt_pk_bf16_f32 v243, v32, v33
	v_cvt_pk_bf16_f32 v244, v26, v27
	v_cvt_pk_bf16_f32 v245, v28, v29
	global_store_dwordx4 v255, v[242:245], s[8:9] offset:256
	s_waitcnt vmcnt(10)
	s_add_u32 s8, s10, 0x90000
	s_addc_u32 s9, s11, 0
	v_lshlrev_b32_e32 v216, 16, v146
	v_and_b32_e32 v217, 0xffff0000, v146
	v_lshlrev_b32_e32 v218, 16, v147
	v_and_b32_e32 v219, 0xffff0000, v147
	v_lshlrev_b32_e32 v220, 16, v148
	v_and_b32_e32 v221, 0xffff0000, v148
	v_lshlrev_b32_e32 v222, 16, v149
	v_and_b32_e32 v223, 0xffff0000, v149
	v_pk_mul_f32 v[216:217], v[216:217], s[86:87] op_sel_hi:[1,0]
	v_pk_mul_f32 v[218:219], v[218:219], s[86:87] op_sel_hi:[1,0]
	v_pk_mul_f32 v[220:221], v[220:221], s[86:87] op_sel_hi:[1,0]
	v_pk_mul_f32 v[222:223], v[222:223], s[86:87] op_sel_hi:[1,0]
	v_exp_f32_e32 v216, v216
	v_exp_f32_e32 v217, v217
	v_exp_f32_e32 v218, v218
	v_exp_f32_e32 v219, v219
	v_exp_f32_e32 v220, v220
	v_exp_f32_e32 v221, v221
	v_exp_f32_e32 v222, v222
	v_exp_f32_e32 v223, v223
	v_pk_add_f32 v[216:217], v[216:217], 1.0 op_sel_hi:[1,0]
	v_pk_add_f32 v[218:219], v[218:219], 1.0 op_sel_hi:[1,0]
	v_pk_add_f32 v[220:221], v[220:221], 1.0 op_sel_hi:[1,0]
	v_pk_add_f32 v[222:223], v[222:223], 1.0 op_sel_hi:[1,0]
	v_rcp_f32_e32 v216, v216
	v_rcp_f32_e32 v217, v217
	v_rcp_f32_e32 v218, v218
	v_rcp_f32_e32 v219, v219
	v_rcp_f32_e32 v220, v220
	v_rcp_f32_e32 v221, v221
	v_rcp_f32_e32 v222, v222
	v_rcp_f32_e32 v223, v223
	s_nop 0
	v_pk_mul_f32 v[54:55], v[54:55], v[216:217]
	v_pk_mul_f32 v[56:57], v[56:57], v[218:219]
	v_pk_mul_f32 v[50:51], v[50:51], v[220:221]
	v_pk_mul_f32 v[52:53], v[52:53], v[222:223]
	v_cvt_pk_bf16_f32 v242, v54, v55
	v_cvt_pk_bf16_f32 v243, v56, v57
	v_cvt_pk_bf16_f32 v244, v50, v51
	v_cvt_pk_bf16_f32 v245, v52, v53
	global_store_dwordx4 v255, v[242:245], s[8:9]
	v_lshlrev_b32_e32 v216, 16, v154
	v_and_b32_e32 v217, 0xffff0000, v154
	v_lshlrev_b32_e32 v218, 16, v155
	v_and_b32_e32 v219, 0xffff0000, v155
	v_lshlrev_b32_e32 v220, 16, v156
	v_and_b32_e32 v221, 0xffff0000, v156
	v_lshlrev_b32_e32 v222, 16, v157
	v_and_b32_e32 v223, 0xffff0000, v157
	v_pk_mul_f32 v[216:217], v[216:217], s[86:87] op_sel_hi:[1,0]
	v_pk_mul_f32 v[218:219], v[218:219], s[86:87] op_sel_hi:[1,0]
	v_pk_mul_f32 v[220:221], v[220:221], s[86:87] op_sel_hi:[1,0]
	v_pk_mul_f32 v[222:223], v[222:223], s[86:87] op_sel_hi:[1,0]
	v_exp_f32_e32 v216, v216
	v_exp_f32_e32 v217, v217
	v_exp_f32_e32 v218, v218
	v_exp_f32_e32 v219, v219
	v_exp_f32_e32 v220, v220
	v_exp_f32_e32 v221, v221
	v_exp_f32_e32 v222, v222
	v_exp_f32_e32 v223, v223
	v_pk_add_f32 v[216:217], v[216:217], 1.0 op_sel_hi:[1,0]
	v_pk_add_f32 v[218:219], v[218:219], 1.0 op_sel_hi:[1,0]
	v_pk_add_f32 v[220:221], v[220:221], 1.0 op_sel_hi:[1,0]
	v_pk_add_f32 v[222:223], v[222:223], 1.0 op_sel_hi:[1,0]
	v_rcp_f32_e32 v216, v216
	v_rcp_f32_e32 v217, v217
	v_rcp_f32_e32 v218, v218
	v_rcp_f32_e32 v219, v219
	v_rcp_f32_e32 v220, v220
	v_rcp_f32_e32 v221, v221
	v_rcp_f32_e32 v222, v222
	v_rcp_f32_e32 v223, v223
	s_nop 0
	v_pk_mul_f32 v[22:23], v[22:23], v[216:217]
	v_pk_mul_f32 v[24:25], v[24:25], v[218:219]
	v_pk_mul_f32 v[18:19], v[18:19], v[220:221]
	v_pk_mul_f32 v[20:21], v[20:21], v[222:223]
	v_cvt_pk_bf16_f32 v242, v22, v23
	v_cvt_pk_bf16_f32 v243, v24, v25
	v_cvt_pk_bf16_f32 v244, v18, v19
	v_cvt_pk_bf16_f32 v245, v20, v21
	global_store_dwordx4 v255, v[242:245], s[8:9] offset:256
	s_waitcnt vmcnt(8)
	s_add_u32 s8, s10, 0xa0000
	s_addc_u32 s9, s11, 0
	v_lshlrev_b32_e32 v216, 16, v162
	v_and_b32_e32 v217, 0xffff0000, v162
	v_lshlrev_b32_e32 v218, 16, v163
	v_and_b32_e32 v219, 0xffff0000, v163
	v_lshlrev_b32_e32 v220, 16, v164
	v_and_b32_e32 v221, 0xffff0000, v164
	v_lshlrev_b32_e32 v222, 16, v165
	v_and_b32_e32 v223, 0xffff0000, v165
	v_pk_mul_f32 v[216:217], v[216:217], s[86:87] op_sel_hi:[1,0]
	v_pk_mul_f32 v[218:219], v[218:219], s[86:87] op_sel_hi:[1,0]
	v_pk_mul_f32 v[220:221], v[220:221], s[86:87] op_sel_hi:[1,0]
	v_pk_mul_f32 v[222:223], v[222:223], s[86:87] op_sel_hi:[1,0]
	v_exp_f32_e32 v216, v216
	v_exp_f32_e32 v217, v217
	v_exp_f32_e32 v218, v218
	v_exp_f32_e32 v219, v219
	v_exp_f32_e32 v220, v220
	v_exp_f32_e32 v221, v221
	v_exp_f32_e32 v222, v222
	v_exp_f32_e32 v223, v223
	v_pk_add_f32 v[216:217], v[216:217], 1.0 op_sel_hi:[1,0]
	v_pk_add_f32 v[218:219], v[218:219], 1.0 op_sel_hi:[1,0]
	v_pk_add_f32 v[220:221], v[220:221], 1.0 op_sel_hi:[1,0]
	v_pk_add_f32 v[222:223], v[222:223], 1.0 op_sel_hi:[1,0]
	v_rcp_f32_e32 v216, v216
	v_rcp_f32_e32 v217, v217
	v_rcp_f32_e32 v218, v218
	v_rcp_f32_e32 v219, v219
	v_rcp_f32_e32 v220, v220
	v_rcp_f32_e32 v221, v221
	v_rcp_f32_e32 v222, v222
	v_rcp_f32_e32 v223, v223
	s_nop 0
	v_pk_mul_f32 v[46:47], v[46:47], v[216:217]
	v_pk_mul_f32 v[48:49], v[48:49], v[218:219]
	v_pk_mul_f32 v[42:43], v[42:43], v[220:221]
	v_pk_mul_f32 v[44:45], v[44:45], v[222:223]
	v_cvt_pk_bf16_f32 v242, v46, v47
	v_cvt_pk_bf16_f32 v243, v48, v49
	v_cvt_pk_bf16_f32 v244, v42, v43
	v_cvt_pk_bf16_f32 v245, v44, v45
	global_store_dwordx4 v255, v[242:245], s[8:9]
	v_lshlrev_b32_e32 v216, 16, v170
	v_and_b32_e32 v217, 0xffff0000, v170
	v_lshlrev_b32_e32 v218, 16, v171
	v_and_b32_e32 v219, 0xffff0000, v171
	v_lshlrev_b32_e32 v220, 16, v172
	v_and_b32_e32 v221, 0xffff0000, v172
	v_lshlrev_b32_e32 v222, 16, v173
	v_and_b32_e32 v223, 0xffff0000, v173
	v_pk_mul_f32 v[216:217], v[216:217], s[86:87] op_sel_hi:[1,0]
	v_pk_mul_f32 v[218:219], v[218:219], s[86:87] op_sel_hi:[1,0]
	v_pk_mul_f32 v[220:221], v[220:221], s[86:87] op_sel_hi:[1,0]
	v_pk_mul_f32 v[222:223], v[222:223], s[86:87] op_sel_hi:[1,0]
	v_exp_f32_e32 v216, v216
	v_exp_f32_e32 v217, v217
	v_exp_f32_e32 v218, v218
	v_exp_f32_e32 v219, v219
	v_exp_f32_e32 v220, v220
	v_exp_f32_e32 v221, v221
	v_exp_f32_e32 v222, v222
	v_exp_f32_e32 v223, v223
	v_pk_add_f32 v[216:217], v[216:217], 1.0 op_sel_hi:[1,0]
	v_pk_add_f32 v[218:219], v[218:219], 1.0 op_sel_hi:[1,0]
	v_pk_add_f32 v[220:221], v[220:221], 1.0 op_sel_hi:[1,0]
	v_pk_add_f32 v[222:223], v[222:223], 1.0 op_sel_hi:[1,0]
	v_rcp_f32_e32 v216, v216
	v_rcp_f32_e32 v217, v217
	v_rcp_f32_e32 v218, v218
	v_rcp_f32_e32 v219, v219
	v_rcp_f32_e32 v220, v220
	v_rcp_f32_e32 v221, v221
	v_rcp_f32_e32 v222, v222
	v_rcp_f32_e32 v223, v223
	s_nop 0
	v_pk_mul_f32 v[14:15], v[14:15], v[216:217]
	v_pk_mul_f32 v[16:17], v[16:17], v[218:219]
	v_pk_mul_f32 v[10:11], v[10:11], v[220:221]
	v_pk_mul_f32 v[12:13], v[12:13], v[222:223]
	v_cvt_pk_bf16_f32 v242, v14, v15
	v_cvt_pk_bf16_f32 v243, v16, v17
	v_cvt_pk_bf16_f32 v244, v10, v11
	v_cvt_pk_bf16_f32 v245, v12, v13
	global_store_dwordx4 v255, v[242:245], s[8:9] offset:256
	s_waitcnt vmcnt(6)
	s_add_u32 s8, s10, 0xb0000
	s_addc_u32 s9, s11, 0
	v_lshlrev_b32_e32 v216, 16, v178
	v_and_b32_e32 v217, 0xffff0000, v178
	v_lshlrev_b32_e32 v218, 16, v179
	v_and_b32_e32 v219, 0xffff0000, v179
	v_lshlrev_b32_e32 v220, 16, v180
	v_and_b32_e32 v221, 0xffff0000, v180
	v_lshlrev_b32_e32 v222, 16, v181
	v_and_b32_e32 v223, 0xffff0000, v181
	v_pk_mul_f32 v[216:217], v[216:217], s[86:87] op_sel_hi:[1,0]
	v_pk_mul_f32 v[218:219], v[218:219], s[86:87] op_sel_hi:[1,0]
	v_pk_mul_f32 v[220:221], v[220:221], s[86:87] op_sel_hi:[1,0]
	v_pk_mul_f32 v[222:223], v[222:223], s[86:87] op_sel_hi:[1,0]
	v_exp_f32_e32 v216, v216
	v_exp_f32_e32 v217, v217
	v_exp_f32_e32 v218, v218
	v_exp_f32_e32 v219, v219
	v_exp_f32_e32 v220, v220
	v_exp_f32_e32 v221, v221
	v_exp_f32_e32 v222, v222
	v_exp_f32_e32 v223, v223
	v_pk_add_f32 v[216:217], v[216:217], 1.0 op_sel_hi:[1,0]
	v_pk_add_f32 v[218:219], v[218:219], 1.0 op_sel_hi:[1,0]
	v_pk_add_f32 v[220:221], v[220:221], 1.0 op_sel_hi:[1,0]
	v_pk_add_f32 v[222:223], v[222:223], 1.0 op_sel_hi:[1,0]
	v_rcp_f32_e32 v216, v216
	v_rcp_f32_e32 v217, v217
	v_rcp_f32_e32 v218, v218
	v_rcp_f32_e32 v219, v219
	v_rcp_f32_e32 v220, v220
	v_rcp_f32_e32 v221, v221
	v_rcp_f32_e32 v222, v222
	v_rcp_f32_e32 v223, v223
	s_nop 0
	v_pk_mul_f32 v[38:39], v[38:39], v[216:217]
	v_pk_mul_f32 v[40:41], v[40:41], v[218:219]
	v_pk_mul_f32 v[34:35], v[34:35], v[220:221]
	v_pk_mul_f32 v[36:37], v[36:37], v[222:223]
	v_cvt_pk_bf16_f32 v242, v38, v39
	v_cvt_pk_bf16_f32 v243, v40, v41
	v_cvt_pk_bf16_f32 v244, v34, v35
	v_cvt_pk_bf16_f32 v245, v36, v37
	global_store_dwordx4 v255, v[242:245], s[8:9]
	v_lshlrev_b32_e32 v216, 16, v186
	v_and_b32_e32 v217, 0xffff0000, v186
	v_lshlrev_b32_e32 v218, 16, v187
	v_and_b32_e32 v219, 0xffff0000, v187
	v_lshlrev_b32_e32 v220, 16, v188
	v_and_b32_e32 v221, 0xffff0000, v188
	v_lshlrev_b32_e32 v222, 16, v189
	v_and_b32_e32 v223, 0xffff0000, v189
	v_pk_mul_f32 v[216:217], v[216:217], s[86:87] op_sel_hi:[1,0]
	v_pk_mul_f32 v[218:219], v[218:219], s[86:87] op_sel_hi:[1,0]
	v_pk_mul_f32 v[220:221], v[220:221], s[86:87] op_sel_hi:[1,0]
	v_pk_mul_f32 v[222:223], v[222:223], s[86:87] op_sel_hi:[1,0]
	v_exp_f32_e32 v216, v216
	v_exp_f32_e32 v217, v217
	v_exp_f32_e32 v218, v218
	v_exp_f32_e32 v219, v219
	v_exp_f32_e32 v220, v220
	v_exp_f32_e32 v221, v221
	v_exp_f32_e32 v222, v222
	v_exp_f32_e32 v223, v223
	v_pk_add_f32 v[216:217], v[216:217], 1.0 op_sel_hi:[1,0]
	v_pk_add_f32 v[218:219], v[218:219], 1.0 op_sel_hi:[1,0]
	v_pk_add_f32 v[220:221], v[220:221], 1.0 op_sel_hi:[1,0]
	v_pk_add_f32 v[222:223], v[222:223], 1.0 op_sel_hi:[1,0]
	v_rcp_f32_e32 v216, v216
	v_rcp_f32_e32 v217, v217
	v_rcp_f32_e32 v218, v218
	v_rcp_f32_e32 v219, v219
	v_rcp_f32_e32 v220, v220
	v_rcp_f32_e32 v221, v221
	v_rcp_f32_e32 v222, v222
	v_rcp_f32_e32 v223, v223
	s_nop 0
	v_pk_mul_f32 v[6:7], v[6:7], v[216:217]
	v_pk_mul_f32 v[8:9], v[8:9], v[218:219]
	v_pk_mul_f32 v[2:3], v[2:3], v[220:221]
	v_pk_mul_f32 v[4:5], v[4:5], v[222:223]
	v_cvt_pk_bf16_f32 v242, v6, v7
	v_cvt_pk_bf16_f32 v243, v8, v9
	v_cvt_pk_bf16_f32 v244, v2, v3
	v_cvt_pk_bf16_f32 v245, v4, v5
	global_store_dwordx4 v255, v[242:245], s[8:9] offset:256
.Lem_done:
.LBB0_465:
	s_mov_b64 s[6:7], -1
	s_and_b64 vcc, exec, s[0:1]
	s_cbranch_vccz .LBB0_364
	s_andn2_b64 vcc, exec, s[52:53]
	s_cbranch_vccnz .LBB0_363
	v_mov_b32_e32 v2, 0
	v_mov_b32_e32 v3, v2
	v_mov_b32_e32 v4, v2
	v_mov_b32_e32 v5, v2
	v_mov_b32_e32 v6, v2
	v_mov_b32_e32 v7, v2
	v_mov_b32_e32 v8, v2
	v_mov_b32_e32 v9, v2
	v_mov_b32_e32 v10, v2
	v_mov_b32_e32 v11, v2
	v_mov_b32_e32 v12, v2
	v_mov_b32_e32 v13, v2
	v_mov_b32_e32 v14, v2
	v_mov_b32_e32 v15, v2
	v_mov_b32_e32 v16, v2
	v_mov_b32_e32 v17, v2
	v_mov_b32_e32 v18, v2
	v_mov_b32_e32 v19, v2
	v_mov_b32_e32 v20, v2
	v_mov_b32_e32 v21, v2
	v_mov_b32_e32 v22, v2
	v_mov_b32_e32 v23, v2
	v_mov_b32_e32 v24, v2
	v_mov_b32_e32 v25, v2
	v_mov_b32_e32 v26, v2
	v_mov_b32_e32 v27, v2
	v_mov_b32_e32 v28, v2
	v_mov_b32_e32 v29, v2
	v_mov_b32_e32 v30, v2
	v_mov_b32_e32 v31, v2
	v_mov_b32_e32 v32, v2
	v_mov_b32_e32 v33, v2
	v_mov_b32_e32 v34, v2
	v_mov_b32_e32 v35, v2
	v_mov_b32_e32 v36, v2
	v_mov_b32_e32 v37, v2
	v_mov_b32_e32 v38, v2
	v_mov_b32_e32 v39, v2
	v_mov_b32_e32 v40, v2
	v_mov_b32_e32 v41, v2
	v_mov_b32_e32 v42, v2
	v_mov_b32_e32 v43, v2
	v_mov_b32_e32 v44, v2
	v_mov_b32_e32 v45, v2
	v_mov_b32_e32 v46, v2
	v_mov_b32_e32 v47, v2
	v_mov_b32_e32 v48, v2
	v_mov_b32_e32 v49, v2
	v_mov_b32_e32 v50, v2
	v_mov_b32_e32 v51, v2
	v_mov_b32_e32 v52, v2
	v_mov_b32_e32 v53, v2
	v_mov_b32_e32 v54, v2
	v_mov_b32_e32 v55, v2
	v_mov_b32_e32 v56, v2
	v_mov_b32_e32 v57, v2
	v_mov_b32_e32 v58, v2
	v_mov_b32_e32 v59, v2
	v_mov_b32_e32 v60, v2
	v_mov_b32_e32 v61, v2
	v_mov_b32_e32 v62, v2
	v_mov_b32_e32 v63, v2
	v_mov_b32_e32 v64, v2
	v_mov_b32_e32 v65, v2
	v_mov_b32_e32 v66, v2
	v_mov_b32_e32 v67, v2
	v_mov_b32_e32 v68, v2
	v_mov_b32_e32 v69, v2
	v_mov_b32_e32 v70, v2
	v_mov_b32_e32 v71, v2
	v_mov_b32_e32 v72, v2
	v_mov_b32_e32 v73, v2
	v_mov_b32_e32 v74, v2
	v_mov_b32_e32 v75, v2
	v_mov_b32_e32 v76, v2
	v_mov_b32_e32 v77, v2
	v_mov_b32_e32 v78, v2
	v_mov_b32_e32 v79, v2
	v_mov_b32_e32 v80, v2
	v_mov_b32_e32 v81, v2
	v_mov_b32_e32 v82, v2
	v_mov_b32_e32 v83, v2
	v_mov_b32_e32 v84, v2
	v_mov_b32_e32 v85, v2
	v_mov_b32_e32 v86, v2
	v_mov_b32_e32 v87, v2
	v_mov_b32_e32 v88, v2
	v_mov_b32_e32 v89, v2
	v_mov_b32_e32 v90, v2
	v_mov_b32_e32 v91, v2
	v_mov_b32_e32 v92, v2
	v_mov_b32_e32 v93, v2
	v_mov_b32_e32 v94, v2
	v_mov_b32_e32 v95, v2
	v_mov_b32_e32 v96, v2
	v_mov_b32_e32 v97, v2
	v_mov_b32_e32 v98, v2
	v_mov_b32_e32 v99, v2
	v_mov_b32_e32 v100, v2
	v_mov_b32_e32 v101, v2
	v_mov_b32_e32 v102, v2
	v_mov_b32_e32 v103, v2
	v_mov_b32_e32 v104, v2
	v_mov_b32_e32 v105, v2
	v_mov_b32_e32 v106, v2
	v_mov_b32_e32 v107, v2
	v_mov_b32_e32 v108, v2
	v_mov_b32_e32 v109, v2
	v_mov_b32_e32 v110, v2
	v_mov_b32_e32 v111, v2
	v_mov_b32_e32 v112, v2
	v_mov_b32_e32 v113, v2
	v_mov_b32_e32 v114, v2
	v_mov_b32_e32 v115, v2
	v_mov_b32_e32 v116, v2
	v_mov_b32_e32 v117, v2
	v_mov_b32_e32 v118, v2
	v_mov_b32_e32 v119, v2
	v_mov_b32_e32 v120, v2
	v_mov_b32_e32 v121, v2
	v_mov_b32_e32 v122, v2
	v_mov_b32_e32 v123, v2
	v_mov_b32_e32 v124, v2
	v_mov_b32_e32 v125, v2
	v_mov_b32_e32 v126, v2
	v_mov_b32_e32 v127, v2
	v_mov_b32_e32 v128, v2
	v_mov_b32_e32 v129, v2
	s_branch .LBB0_363
